# scan loop v2 (packed cvt, unroll 4) + EpiRes epilogue residual-load prefetch ring + rstd table loop split across both wave halves
# speedup vs baseline: 1.0156x; 1.0156x over previous
; __device__ __forceinline__ int opaque_tid() { int t = threadIdx.x; asm volatile("" : "+v"(t)); return t; }
; __device__ __forceinline__ int opaque_bid() { int b = blockIdx.x; asm volatile("" : "+s"(b)); return b; }
; template <class Epi>
; __device__ __forceinline__ void run_gemm_norm(unsigned char* lds, const bf16* A, const bf16* Bt, int M, int N, int K, const Epi& E, const float* ssq) {
;     { asm volatile("" : "+s"(N));
;       float* tab = (float*)(lds + RSTD_OFF); const int tid = opaque_tid();
;       pg8::StaticOrder S; S.init(M, N, (int)gridDim.x, opaque_bid()); pg8::Unit u;
;       for (int i = 0; i < 15 && S.next(i, u); ++i) if (tid < 256) tab[i * 256 + tid] = row_rstd(ssq, u.pm * 256 + tid);
;       __syncthreads(); }
.LBB0_85:
	s_lshr_b32 s23, s14, 1
	s_bitcmp1_b32 s14, 0
	s_cselect_b64 s[10:11], -1, 0
	s_and_b64 vcc, exec, s[10:11]
	s_mov_b64 s[0:1], -1
	v_writelane_b32 v239, s14, 38
	s_nop 1
	v_writelane_b32 v239, s15, 39
	s_cbranch_vccz .LBB0_167
	s_mov_b64 s[0:1], s[68:69]
	s_load_dwordx2 s[2:3], s[0:1], 0xd0
	s_lshl_b32 s0, s14, 21
	s_mov_b64 s[60:61], s[10:11]
	s_movk_i32 s10, 0x1600
	s_waitcnt lgkmcnt(0)
	s_add_u32 s0, s2, s0
	s_addc_u32 s1, s3, 0
	s_add_u32 s4, s0, 0x1d200000
	s_addc_u32 s5, s1, 0
	s_ashr_i32 s0, s10, 31
	s_lshr_b32 s0, s0, 24
	s_add_i32 s14, s10, s0
	s_ashr_i32 s0, s14, 8
	s_lshl_b32 s11, s0, 2
	s_abs_i32 s12, s11
	v_cvt_f32_u32_e32 v2, s12
	s_sub_i32 s15, 0, s12
	s_lshl_b32 s8, s0, 7
	v_mov_b32_e32 v0, v162
	v_rcp_iflag_f32_e32 v2, v2
	s_mov_b32 s6, s67
	s_ashr_i32 s9, s8, 31
	s_lshl_b32 s13, s0, 4
	v_mul_f32_e32 v2, 0x4f7ffffe, v2
	v_cvt_u32_f32_e32 v2, v2
	s_movk_i32 s0, 0x100
	v_readfirstlane_b32 s16, v2
	s_mul_i32 s15, s15, s16
	s_mul_hi_u32 s15, s16, s15
	s_add_i32 s15, s16, s15
	v_readlane_b32 s16, v240, 42
	s_ashr_i32 s7, s6, 31
	s_mov_b64 s[0:1], exec
	s_ashr_i32 s14, s14, 31
	v_and_b32_e32 v42, 0xff, v0
	v_readfirstlane_b32 s38, v0
	v_lshl_add_u32 v4, v42, 2, s16
	s_movk_i32 s16, 0xc400
	v_mov_b64_e32 v[2:3], s[8:9]
	s_lshr_b32 s38, s38, 8
	s_cmp_eq_u32 s38, 0
	s_cbranch_scc1 .Lrstd_a_lo
	s_addk_i32 s16, 0x400
	s_add_u32 s6, s6, s70
	s_addc_u32 s7, s7, s71
.Lrstd_a_lo:
	s_branch .LBB0_89
.LBB0_87:
	s_or_b64 exec, exec, s[8:9]
	s_addk_i32 s16, 0x800
	s_add_u32 s6, s6, s70
	s_addc_u32 s7, s7, s71
	s_add_u32 s6, s6, s70
	s_addc_u32 s7, s7, s71
	s_cmp_ge_i32 s16, 0
	s_cselect_b64 s[8:9], -1, 0

;     __host__ __device__ bool next(int i, Unit& u) const {
;         const long L = (long)i * G + c; if (L >= nwg) return false;
;         int wgid = (int)L; { const int q = nwg / NXCD, r = nwg % NXCD, xcd = wgid % NXCD, off = wgid / NXCD; wgid = (xcd < r ? xcd * (q + 1) : r * (q + 1) + (xcd - r) * q) + off; }
;         const int nig = WGM * nN, gid = wgid / nig, fm = gid * WGM, gsz = (nM - fm) < WGM ? (nM - fm) : WGM;
;         u.pm = fm + ((wgid % nig) % gsz); u.pn = (wgid % nig) / gsz; return true;
;     }
; __device__ __forceinline__ float row_rstd(const float* ssq, int row) {
;     const f32x4* q = (const f32x4*)(ssq + (size_t)row * 16); const f32x4 a = q[0], b = q[1], c = q[2], d = q[3];
;     const float s = ((a[0] + a[1]) + (a[2] + a[3])) + ((b[0] + b[1]) + (b[2] + b[3])) + ((c[0] + c[1]) + (c[2] + c[3])) + ((d[0] + d[1]) + (d[2] + d[3]));
;     return rsqrtf(s * (1.f / DM) + 1e-6f);
; }
.LBB0_89:
	v_cmp_ge_i64_e32 vcc, s[6:7], v[2:3]
	s_mov_b64 s[8:9], -1
	s_cbranch_vccnz .LBB0_88
	s_and_saveexec_b64 s[8:9], s[0:1]
	s_cbranch_execz .LBB0_87
	s_ashr_i32 s17, s6, 31
	s_lshr_b32 s17, s17, 29
	s_add_i32 s17, s6, s17
	s_ashr_i32 s18, s17, 3
	s_and_b32 s17, s17, -8
	s_sub_i32 s17, s6, s17
	s_lshr_b32 s19, s17, 31
	s_or_b32 s19, s19, s13
	s_mul_i32 s17, s19, s17
	s_add_i32 s17, s17, s18
	s_abs_i32 s19, s17
	s_mul_hi_u32 s20, s19, s15
	s_mul_i32 s21, s20, s12
	s_ashr_i32 s18, s17, 31
	s_sub_i32 s19, s19, s21
	s_xor_b32 s18, s18, s14
	s_add_i32 s21, s20, 1
	s_sub_i32 s22, s19, s12
	s_cmp_ge_u32 s19, s12
	s_cselect_b32 s20, s21, s20
	s_cselect_b32 s19, s22, s19
	s_add_i32 s21, s20, 1
	s_cmp_ge_u32 s19, s12
	s_cselect_b32 s19, s21, s20
	s_xor_b32 s19, s19, s18
	s_sub_i32 s18, s19, s18
	s_mul_i32 s19, s18, s11
	s_lshl_b32 s18, s18, 2
	s_sub_i32 s17, s17, s19
	s_sub_i32 s19, 0x80, s18
	s_min_i32 s19, s19, 4
	s_abs_i32 s19, s19
	v_cvt_f32_u32_e32 v5, s19
	s_sub_i32 s21, 0, s19
	s_ashr_i32 s20, s17, 31
	s_abs_i32 s17, s17
	v_rcp_iflag_f32_e32 v5, v5
	s_nop 0
	v_mul_f32_e32 v5, 0x4f7ffffe, v5
	v_cvt_u32_f32_e32 v5, v5
	s_nop 0
	v_readfirstlane_b32 s22, v5
	s_mul_i32 s21, s21, s22
	s_mul_hi_u32 s21, s22, s21
	s_add_i32 s22, s22, s21
	s_mul_hi_u32 s21, s17, s22
	s_mul_i32 s21, s21, s19
	s_sub_i32 s17, s17, s21
	s_sub_i32 s21, s17, s19
	s_cmp_ge_u32 s17, s19
	s_cselect_b32 s17, s21, s17
	s_sub_i32 s21, s17, s19
	s_cmp_ge_u32 s17, s19
	s_cselect_b32 s17, s21, s17
	s_xor_b32 s17, s17, s20
	s_sub_i32 s17, s17, s20
	s_add_i32 s17, s17, s18
	v_lshl_add_u32 v6, s17, 8, v42
	v_ashrrev_i32_e32 v7, 31, v6
	v_lshlrev_b64 v[6:7], 6, v[6:7]
	v_lshl_add_u64 v[18:19], s[4:5], 0, v[6:7]
	global_load_dwordx4 v[6:9], v[18:19], off offset:48
	global_load_dwordx4 v[10:13], v[18:19], off offset:32
	global_load_dwordx4 v[14:17], v[18:19], off offset:16
	s_nop 0
	global_load_dwordx4 v[18:21], v[18:19], off
	s_waitcnt vmcnt(2)
	v_add_f32_e32 v10, v10, v11
	v_add_f32_e32 v12, v12, v13
	s_waitcnt vmcnt(0)
	v_mov_b32_e32 v22, v19
	v_mov_b32_e32 v23, v20
	v_mov_b32_e32 v19, v21
	v_mov_b32_e32 v20, v15
	v_mov_b32_e32 v21, v16
	v_mov_b32_e32 v15, v17
	v_pk_add_f32 v[18:19], v[22:23], v[18:19]
	v_pk_add_f32 v[14:15], v[20:21], v[14:15]
	v_pk_add_f32 v[18:19], v[18:19], v[18:19] op_sel:[0,1] op_sel_hi:[1,0]
	v_pk_add_f32 v[14:15], v[14:15], v[14:15] op_sel:[0,1] op_sel_hi:[1,0]
	v_mov_b32_e32 v19, v6
	v_mov_b32_e32 v15, v7
	v_mov_b32_e32 v11, v8
	v_mov_b32_e32 v13, v9
	v_pk_add_f32 v[6:7], v[18:19], v[14:15]
	v_pk_add_f32 v[8:9], v[10:11], v[12:13]
	s_nop 0
	v_pk_add_f32 v[6:7], v[6:7], v[8:9]
	s_nop 0
	v_add_f32_e32 v5, v6, v7
	v_fmamk_f32 v5, v5, 0x3a800000, v164
	v_cmp_gt_f32_e32 vcc, s35, v5
	v_mul_f32_e32 v6, 0x4b800000, v5
	s_nop 0
	v_cndmask_b32_e32 v5, v5, v6, vcc
	v_rsq_f32_e32 v5, v5
	s_nop 0
	v_mul_f32_e32 v6, 0x45800000, v5
	v_cndmask_b32_e32 v5, v5, v6, vcc
	v_add_u32_e32 v6, s16, v4
	ds_write_b32 v6, v5 offset:15360
	s_branch .LBB0_87

; __device__ __forceinline__ int opaque_tid() { int t = threadIdx.x; asm volatile("" : "+v"(t)); return t; }
; __device__ __forceinline__ int opaque_bid() { int b = blockIdx.x; asm volatile("" : "+s"(b)); return b; }
; template <class Epi>
; __device__ __forceinline__ void run_gemm_norm(unsigned char* lds, const bf16* A, const bf16* Bt, int M, int N, int K, const Epi& E, const float* ssq) {
;     { asm volatile("" : "+s"(N));
;       float* tab = (float*)(lds + RSTD_OFF); const int tid = opaque_tid();
;       pg8::StaticOrder S; S.init(M, N, (int)gridDim.x, opaque_bid()); pg8::Unit u;
;       for (int i = 0; i < 15 && S.next(i, u); ++i) if (tid < 256) tab[i * 256 + tid] = row_rstd(ssq, u.pm * 256 + tid);
;       __syncthreads(); }
.LBB0_170:
	s_load_dwordx2 s[2:3], s[0:1], 0xd0
	s_and_b64 s[0:1], exec, s[14:15]
	v_writelane_b32 v239, s8, 43
	s_movk_i32 s0, 0xf00
	s_cselect_b32 s34, s0, 0x600
	v_readlane_b32 s0, v239, 38
	s_lshl_b32 s0, s0, 21
	v_readlane_b32 s1, v239, 39
	s_waitcnt lgkmcnt(0)
	s_add_u32 s0, s2, s0
	s_addc_u32 s1, s3, 0
	s_mov_b32 s18, s34
	s_add_u32 s8, s0, 0x1d200000
	s_addc_u32 s9, s1, 0
	s_ashr_i32 s0, s18, 31
	s_lshr_b32 s0, s0, 24
	s_add_i32 s16, s18, s0
	s_ashr_i32 s0, s16, 8
	s_lshl_b32 s19, s0, 2
	s_abs_i32 s20, s19
	v_cvt_f32_u32_e32 v2, s20
	s_ashr_i32 s22, s16, 31
	s_sub_i32 s16, 0, s20
	v_mov_b32_e32 v0, v162
	v_rcp_iflag_f32_e32 v2, v2
	s_mov_b32 s10, s67
	s_lshl_b32 s12, s0, 7
	s_lshl_b32 s21, s0, 4
	v_mul_f32_e32 v2, 0x4f7ffffe, v2
	v_cvt_u32_f32_e32 v2, v2
	s_movk_i32 s0, 0x100
	s_mov_b32 s89, s25
	v_readfirstlane_b32 s17, v2
	s_mul_i32 s16, s16, s17
	s_mul_hi_u32 s16, s17, s16
	s_add_i32 s23, s17, s16
	v_readlane_b32 s16, v240, 42
	s_ashr_i32 s11, s10, 31
	s_ashr_i32 s13, s12, 31
	s_mov_b64 s[0:1], exec
	v_and_b32_e32 v42, 0xff, v0
	v_readfirstlane_b32 s38, v0
	v_lshl_add_u32 v2, v42, 2, s16
	s_movk_i32 s24, 0xc400
	s_lshr_b32 s38, s38, 8
	s_cmp_eq_u32 s38, 0
	s_cbranch_scc1 .Lrstd_b_lo
	s_addk_i32 s24, 0x400
	s_add_u32 s10, s10, s70
	s_addc_u32 s11, s11, s71

; template <class Epi>
; __device__ __forceinline__ void run_gemm_norm(unsigned char* lds, const bf16* A, const bf16* Bt, int M, int N, int K, const Epi& E, const float* ssq) {
;     ...
;       for (int i = 0; i < 15 && S.next(i, u); ++i) if (tid < 256) tab[i * 256 + tid] = row_rstd(ssq, u.pm * 256 + tid);
.LBB0_171:
	s_or_b64 exec, exec, s[16:17]
	s_addk_i32 s24, 0x800
	s_add_u32 s10, s10, s70
	s_addc_u32 s11, s11, s71
	s_add_u32 s10, s10, s70
	s_addc_u32 s11, s11, s71
	s_cmp_ge_i32 s24, 0
	s_cselect_b64 s[16:17], -1, 0

;     __host__ __device__ bool next(int i, Unit& u) const {
;         const long L = (long)i * G + c; if (L >= nwg) return false;
;         int wgid = (int)L; { const int q = nwg / NXCD, r = nwg % NXCD, xcd = wgid % NXCD, off = wgid / NXCD; wgid = (xcd < r ? xcd * (q + 1) : r * (q + 1) + (xcd - r) * q) + off; }
;         const int nig = WGM * nN, gid = wgid / nig, fm = gid * WGM, gsz = (nM - fm) < WGM ? (nM - fm) : WGM;
;         u.pm = fm + ((wgid % nig) % gsz); u.pn = (wgid % nig) / gsz; return true;
;     }
; __device__ __forceinline__ float row_rstd(const float* ssq, int row) {
;     const f32x4* q = (const f32x4*)(ssq + (size_t)row * 16); const f32x4 a = q[0], b = q[1], c = q[2], d = q[3];
;     const float s = ((a[0] + a[1]) + (a[2] + a[3])) + ((b[0] + b[1]) + (b[2] + b[3])) + ((c[0] + c[1]) + (c[2] + c[3])) + ((d[0] + d[1]) + (d[2] + d[3]));
;     return rsqrtf(s * (1.f / DM) + 1e-6f);
; }
.LBB0_173:
	v_mov_b64_e32 v[4:5], s[12:13]
	v_cmp_ge_i64_e32 vcc, s[10:11], v[4:5]
	s_mov_b64 s[16:17], -1
	s_cbranch_vccnz .LBB0_172
	s_and_saveexec_b64 s[16:17], s[0:1]
	s_cbranch_execz .LBB0_171
	s_ashr_i32 s25, s10, 31
	s_lshr_b32 s25, s25, 29
	s_add_i32 s25, s10, s25
	s_ashr_i32 s26, s25, 3
	s_and_b32 s25, s25, -8
	s_sub_i32 s25, s10, s25
	s_lshr_b32 s27, s25, 31
	s_or_b32 s27, s27, s21
	s_mul_i32 s25, s27, s25
	s_add_i32 s25, s25, s26
	s_abs_i32 s27, s25
	s_mul_hi_u32 s28, s27, s23
	s_mul_i32 s29, s28, s20
	s_ashr_i32 s26, s25, 31
	s_sub_i32 s27, s27, s29
	s_xor_b32 s26, s26, s22
	s_add_i32 s29, s28, 1
	s_sub_i32 s30, s27, s20
	s_cmp_ge_u32 s27, s20
	s_cselect_b32 s28, s29, s28
	s_cselect_b32 s27, s30, s27
	s_add_i32 s29, s28, 1
	s_cmp_ge_u32 s27, s20
	s_cselect_b32 s27, s29, s28
	s_xor_b32 s27, s27, s26
	s_sub_i32 s26, s27, s26
	s_mul_i32 s27, s26, s19
	s_lshl_b32 s26, s26, 2
	s_sub_i32 s25, s25, s27
	s_sub_i32 s27, 0x80, s26
	s_min_i32 s27, s27, 4
	s_abs_i32 s27, s27
	v_cvt_f32_u32_e32 v3, s27
	s_sub_i32 s29, 0, s27
	s_ashr_i32 s28, s25, 31
	s_abs_i32 s25, s25
	v_rcp_iflag_f32_e32 v3, v3
	s_nop 0
	v_mul_f32_e32 v3, 0x4f7ffffe, v3
	v_cvt_u32_f32_e32 v3, v3
	s_nop 0
	v_readfirstlane_b32 s30, v3
	s_mul_i32 s29, s29, s30
	s_mul_hi_u32 s29, s30, s29
	s_add_i32 s30, s30, s29
	s_mul_hi_u32 s29, s25, s30
	s_mul_i32 s29, s29, s27
	s_sub_i32 s25, s25, s29
	s_sub_i32 s29, s25, s27
	s_cmp_ge_u32 s25, s27
	s_cselect_b32 s25, s29, s25
	s_sub_i32 s29, s25, s27
	s_cmp_ge_u32 s25, s27
	s_cselect_b32 s25, s29, s25
	s_xor_b32 s25, s25, s28
	s_sub_i32 s25, s25, s28
	s_add_i32 s25, s25, s26
	v_lshl_add_u32 v4, s25, 8, v42
	v_ashrrev_i32_e32 v5, 31, v4
	v_lshlrev_b64 v[4:5], 6, v[4:5]
	v_lshl_add_u64 v[16:17], s[8:9], 0, v[4:5]
	global_load_dwordx4 v[4:7], v[16:17], off offset:48
	global_load_dwordx4 v[8:11], v[16:17], off offset:32
	global_load_dwordx4 v[12:15], v[16:17], off offset:16
	s_nop 0
	global_load_dwordx4 v[16:19], v[16:17], off
	s_waitcnt vmcnt(2)
	v_add_f32_e32 v8, v8, v9
	v_add_f32_e32 v10, v10, v11
	s_waitcnt vmcnt(0)
	v_mov_b32_e32 v20, v17
	v_mov_b32_e32 v21, v18
	v_mov_b32_e32 v17, v19
	v_mov_b32_e32 v18, v13
	v_mov_b32_e32 v19, v14
	v_mov_b32_e32 v13, v15
	v_pk_add_f32 v[16:17], v[20:21], v[16:17]
	v_pk_add_f32 v[12:13], v[18:19], v[12:13]
	v_pk_add_f32 v[16:17], v[16:17], v[16:17] op_sel:[0,1] op_sel_hi:[1,0]
	v_pk_add_f32 v[12:13], v[12:13], v[12:13] op_sel:[0,1] op_sel_hi:[1,0]
	v_mov_b32_e32 v17, v4
	v_mov_b32_e32 v13, v5
	v_mov_b32_e32 v9, v6
	v_mov_b32_e32 v11, v7
	v_pk_add_f32 v[4:5], v[16:17], v[12:13]
	v_pk_add_f32 v[6:7], v[8:9], v[10:11]
	s_nop 0
	v_pk_add_f32 v[4:5], v[4:5], v[6:7]
	s_nop 0
	v_add_f32_e32 v3, v4, v5
	v_fmamk_f32 v3, v3, 0x3a800000, v164
	v_cmp_gt_f32_e32 vcc, s35, v3
	v_mul_f32_e32 v4, 0x4b800000, v3
	s_nop 0
	v_cndmask_b32_e32 v3, v3, v4, vcc
	v_rsq_f32_e32 v3, v3
	s_nop 0
	v_mul_f32_e32 v4, 0x45800000, v3
	v_cndmask_b32_e32 v3, v3, v4, vcc
	v_add_u32_e32 v4, s24, v2
	ds_write_b32 v4, v3 offset:15360
	s_branch .LBB0_171

.LBB0_441:
	v_add_u32_e32 v183, s39, v145
	v_add_u32_e32 v182, s39, v147
	s_mov_b32 s37, 0
	ds_read_b128 v[74:77], v183 offset:0
	ds_read_b128 v[66:69], v183 offset:4096
	ds_read_b128 v[62:65], v183 offset:8192
	ds_read_b128 v[70:73], v183 offset:12288
	ds_read_b32 v184, v182 offset:20480
	ds_read_b128 v[58:61], v183 offset:16384
	s_waitcnt lgkmcnt(1)
	ds_read_b128 v[94:97], v183 offset:128
	ds_read_b128 v[86:89], v183 offset:4224
	ds_read_b128 v[82:85], v183 offset:8320
	ds_read_b128 v[90:93], v183 offset:12416
	ds_read_b32 v185, v182 offset:20736
	ds_read_b128 v[78:81], v183 offset:16512
	v_dot2_f32_f16 v186, v113, v74, 0
	v_dot2_f32_f16 v187, v175, v74, 0
	v_dot2_f32_f16 v186, v178, v75, v186
	v_dot2_f32_f16 v187, v174, v75, v187
	v_dot2_f32_f16 v186, v177, v76, v186
	v_dot2_f32_f16 v187, v161, v76, v187
	v_dot2_f32_f16 v186, v176, v77, v186
	v_dot2_f32_f16 v187, v160, v77, v187
	v_pk_mul_f16 v190, v184, v70
	v_pk_mul_f16 v191, v184, v71
	v_pk_mul_f16 v192, v184, v72
	v_pk_mul_f16 v193, v184, v73
	v_add_f32_dpp v186, v186, v186 quad_perm:[1,0,3,2] row_mask:0xf bank_mask:0xf bound_ctrl:1
	v_add_f32_dpp v187, v187, v187 quad_perm:[1,0,3,2] row_mask:0xf bank_mask:0xf bound_ctrl:1
	v_pk_fma_f16 v113, v113, v62, v190
	v_pk_fma_f16 v178, v178, v63, v191
	v_pk_fma_f16 v177, v177, v64, v192
	v_pk_fma_f16 v176, v176, v65, v193
	v_add_f32_dpp v186, v186, v186 quad_perm:[2,3,0,1] row_mask:0xf bank_mask:0xf bound_ctrl:1
	v_add_f32_dpp v187, v187, v187 quad_perm:[2,3,0,1] row_mask:0xf bank_mask:0xf bound_ctrl:1
	v_pk_mul_f16 v175, v175, v62
	v_pk_mul_f16 v174, v174, v63
	v_pk_mul_f16 v161, v161, v64
	v_pk_mul_f16 v160, v160, v65
	v_add_f32_dpp v186, v186, v186 row_half_mirror row_mask:0xf bank_mask:0xf bound_ctrl:1
	v_add_f32_dpp v187, v187, v187 row_half_mirror row_mask:0xf bank_mask:0xf bound_ctrl:1
	v_cvt_pk_f16_f32 v186, v186, v187
	v_pk_fma_f16 v113, v186, v66, v113 op_sel_hi:[0,1,1]
	v_pk_fma_f16 v175, v186, v66, v175 op_sel:[1,0,0] op_sel_hi:[1,1,1]
	v_pk_fma_f16 v178, v186, v67, v178 op_sel_hi:[0,1,1]
	v_pk_fma_f16 v174, v186, v67, v174 op_sel:[1,0,0] op_sel_hi:[1,1,1]
	v_pk_fma_f16 v177, v186, v68, v177 op_sel_hi:[0,1,1]
	v_pk_fma_f16 v161, v186, v68, v161 op_sel:[1,0,0] op_sel_hi:[1,1,1]
	v_pk_fma_f16 v176, v186, v69, v176 op_sel_hi:[0,1,1]
	v_pk_fma_f16 v160, v186, v69, v160 op_sel:[1,0,0] op_sel_hi:[1,1,1]
.Lscan_loop:
	s_waitcnt lgkmcnt(1)
	ds_read_b128 v[74:77], v183 offset:256
	ds_read_b128 v[66:69], v183 offset:4352
	ds_read_b128 v[62:65], v183 offset:8448
	ds_read_b128 v[70:73], v183 offset:12544
	ds_read_b32 v184, v182 offset:20992
	v_dot2_f32_f16 v186, v113, v94, 0
	v_dot2_f32_f16 v187, v175, v94, 0
	v_dot2_f32_f16 v186, v178, v95, v186
	v_dot2_f32_f16 v187, v174, v95, v187
	v_dot2_f32_f16 v186, v177, v96, v186
	v_dot2_f32_f16 v187, v161, v96, v187
	v_dot2_f32_f16 v186, v176, v97, v186
	v_dot2_f32_f16 v187, v160, v97, v187
	v_dot2_f32_f16 v188, v113, v58, 0
	v_dot2_f32_f16 v189, v175, v58, 0
	v_dot2_f32_f16 v188, v178, v59, v188
	v_dot2_f32_f16 v189, v174, v59, v189
	v_dot2_f32_f16 v188, v177, v60, v188
	v_dot2_f32_f16 v189, v161, v60, v189
	v_dot2_f32_f16 v188, v176, v61, v188
	v_dot2_f32_f16 v189, v160, v61, v189
	ds_read_b128 v[58:61], v183 offset:16640
	v_add_f32_dpp v186, v186, v186 quad_perm:[1,0,3,2] row_mask:0xf bank_mask:0xf bound_ctrl:1
	v_add_f32_dpp v187, v187, v187 quad_perm:[1,0,3,2] row_mask:0xf bank_mask:0xf bound_ctrl:1
	v_add_f32_dpp v188, v188, v188 quad_perm:[1,0,3,2] row_mask:0xf bank_mask:0xf bound_ctrl:1
	v_add_f32_dpp v189, v189, v189 quad_perm:[1,0,3,2] row_mask:0xf bank_mask:0xf bound_ctrl:1
	v_pk_mul_f16 v190, v185, v90
	v_pk_mul_f16 v191, v185, v91
	v_pk_mul_f16 v192, v185, v92
	v_pk_mul_f16 v193, v185, v93
	v_add_f32_dpp v186, v186, v186 quad_perm:[2,3,0,1] row_mask:0xf bank_mask:0xf bound_ctrl:1
	v_add_f32_dpp v187, v187, v187 quad_perm:[2,3,0,1] row_mask:0xf bank_mask:0xf bound_ctrl:1
	v_add_f32_dpp v188, v188, v188 quad_perm:[2,3,0,1] row_mask:0xf bank_mask:0xf bound_ctrl:1
	v_add_f32_dpp v189, v189, v189 quad_perm:[2,3,0,1] row_mask:0xf bank_mask:0xf bound_ctrl:1
	v_pk_fma_f16 v113, v113, v82, v190
	v_pk_fma_f16 v178, v178, v83, v191
	v_pk_fma_f16 v177, v177, v84, v192
	v_pk_fma_f16 v176, v176, v85, v193
	v_pk_mul_f16 v175, v175, v82
	v_pk_mul_f16 v174, v174, v83
	v_pk_mul_f16 v161, v161, v84
	v_pk_mul_f16 v160, v160, v85
	v_add_f32_dpp v186, v186, v186 row_half_mirror row_mask:0xf bank_mask:0xf bound_ctrl:1
	v_add_f32_dpp v187, v187, v187 row_half_mirror row_mask:0xf bank_mask:0xf bound_ctrl:1
	v_add_f32_dpp v188, v188, v188 row_half_mirror row_mask:0xf bank_mask:0xf bound_ctrl:1
	v_add_f32_dpp v189, v189, v189 row_half_mirror row_mask:0xf bank_mask:0xf bound_ctrl:1
	v_cvt_pk_f16_f32 v186, v186, v187
	v_pk_fma_f16 v113, v186, v86, v113 op_sel_hi:[0,1,1]
	v_pk_fma_f16 v175, v186, v86, v175 op_sel:[1,0,0] op_sel_hi:[1,1,1]
	v_pk_fma_f16 v178, v186, v87, v178 op_sel_hi:[0,1,1]
	v_pk_fma_f16 v174, v186, v87, v174 op_sel:[1,0,0] op_sel_hi:[1,1,1]
	v_pk_fma_f16 v177, v186, v88, v177 op_sel_hi:[0,1,1]
	v_pk_fma_f16 v161, v186, v88, v161 op_sel:[1,0,0] op_sel_hi:[1,1,1]
	v_pk_fma_f16 v176, v186, v89, v176 op_sel_hi:[0,1,1]
	v_pk_fma_f16 v160, v186, v89, v160 op_sel:[1,0,0] op_sel_hi:[1,1,1]
	s_and_saveexec_b64 s[30:31], s[2:3]
	ds_write2st64_b32 v182, v189, v188 offset0:112 offset1:144
	s_or_b64 exec, exec, s[30:31]
	s_waitcnt lgkmcnt(1)
	ds_read_b128 v[94:97], v183 offset:384
	ds_read_b128 v[86:89], v183 offset:4480
	ds_read_b128 v[82:85], v183 offset:8576
	ds_read_b128 v[90:93], v183 offset:12672
	ds_read_b32 v185, v182 offset:21248
	v_dot2_f32_f16 v186, v113, v74, 0
	v_dot2_f32_f16 v187, v175, v74, 0
	v_dot2_f32_f16 v186, v178, v75, v186
	v_dot2_f32_f16 v187, v174, v75, v187
	v_dot2_f32_f16 v186, v177, v76, v186
	v_dot2_f32_f16 v187, v161, v76, v187
	v_dot2_f32_f16 v186, v176, v77, v186
	v_dot2_f32_f16 v187, v160, v77, v187
	v_dot2_f32_f16 v188, v113, v78, 0
	v_dot2_f32_f16 v189, v175, v78, 0
	v_dot2_f32_f16 v188, v178, v79, v188
	v_dot2_f32_f16 v189, v174, v79, v189
	v_dot2_f32_f16 v188, v177, v80, v188
	v_dot2_f32_f16 v189, v161, v80, v189
	v_dot2_f32_f16 v188, v176, v81, v188
	v_dot2_f32_f16 v189, v160, v81, v189
	ds_read_b128 v[78:81], v183 offset:16768
	v_add_f32_dpp v186, v186, v186 quad_perm:[1,0,3,2] row_mask:0xf bank_mask:0xf bound_ctrl:1
	v_add_f32_dpp v187, v187, v187 quad_perm:[1,0,3,2] row_mask:0xf bank_mask:0xf bound_ctrl:1
	v_add_f32_dpp v188, v188, v188 quad_perm:[1,0,3,2] row_mask:0xf bank_mask:0xf bound_ctrl:1
	v_add_f32_dpp v189, v189, v189 quad_perm:[1,0,3,2] row_mask:0xf bank_mask:0xf bound_ctrl:1
	v_pk_mul_f16 v190, v184, v70
	v_pk_mul_f16 v191, v184, v71
	v_pk_mul_f16 v192, v184, v72
	v_pk_mul_f16 v193, v184, v73
	v_add_f32_dpp v186, v186, v186 quad_perm:[2,3,0,1] row_mask:0xf bank_mask:0xf bound_ctrl:1
	v_add_f32_dpp v187, v187, v187 quad_perm:[2,3,0,1] row_mask:0xf bank_mask:0xf bound_ctrl:1
	v_add_f32_dpp v188, v188, v188 quad_perm:[2,3,0,1] row_mask:0xf bank_mask:0xf bound_ctrl:1
	v_add_f32_dpp v189, v189, v189 quad_perm:[2,3,0,1] row_mask:0xf bank_mask:0xf bound_ctrl:1
	v_pk_fma_f16 v113, v113, v62, v190
	v_pk_fma_f16 v178, v178, v63, v191
	v_pk_fma_f16 v177, v177, v64, v192
	v_pk_fma_f16 v176, v176, v65, v193
	v_pk_mul_f16 v175, v175, v62
	v_pk_mul_f16 v174, v174, v63
	v_pk_mul_f16 v161, v161, v64
	v_pk_mul_f16 v160, v160, v65
	v_add_f32_dpp v186, v186, v186 row_half_mirror row_mask:0xf bank_mask:0xf bound_ctrl:1
	v_add_f32_dpp v187, v187, v187 row_half_mirror row_mask:0xf bank_mask:0xf bound_ctrl:1
	v_add_f32_dpp v188, v188, v188 row_half_mirror row_mask:0xf bank_mask:0xf bound_ctrl:1
	v_add_f32_dpp v189, v189, v189 row_half_mirror row_mask:0xf bank_mask:0xf bound_ctrl:1
	v_cvt_pk_f16_f32 v186, v186, v187
	v_pk_fma_f16 v113, v186, v66, v113 op_sel_hi:[0,1,1]
	v_pk_fma_f16 v175, v186, v66, v175 op_sel:[1,0,0] op_sel_hi:[1,1,1]
	v_pk_fma_f16 v178, v186, v67, v178 op_sel_hi:[0,1,1]
	v_pk_fma_f16 v174, v186, v67, v174 op_sel:[1,0,0] op_sel_hi:[1,1,1]
	v_pk_fma_f16 v177, v186, v68, v177 op_sel_hi:[0,1,1]
	v_pk_fma_f16 v161, v186, v68, v161 op_sel:[1,0,0] op_sel_hi:[1,1,1]
	v_pk_fma_f16 v176, v186, v69, v176 op_sel_hi:[0,1,1]
	v_pk_fma_f16 v160, v186, v69, v160 op_sel:[1,0,0] op_sel_hi:[1,1,1]
	s_and_saveexec_b64 s[30:31], s[2:3]
	ds_write2st64_b32 v182, v189, v188 offset0:113 offset1:145
	s_or_b64 exec, exec, s[30:31]
	s_waitcnt lgkmcnt(1)
	ds_read_b128 v[74:77], v183 offset:512
	ds_read_b128 v[66:69], v183 offset:4608
	ds_read_b128 v[62:65], v183 offset:8704
	ds_read_b128 v[70:73], v183 offset:12800
	ds_read_b32 v184, v182 offset:21504
	v_dot2_f32_f16 v186, v113, v94, 0
	v_dot2_f32_f16 v187, v175, v94, 0
	v_dot2_f32_f16 v186, v178, v95, v186
	v_dot2_f32_f16 v187, v174, v95, v187
	v_dot2_f32_f16 v186, v177, v96, v186
	v_dot2_f32_f16 v187, v161, v96, v187
	v_dot2_f32_f16 v186, v176, v97, v186
	v_dot2_f32_f16 v187, v160, v97, v187
	v_dot2_f32_f16 v188, v113, v58, 0
	v_dot2_f32_f16 v189, v175, v58, 0
	v_dot2_f32_f16 v188, v178, v59, v188
	v_dot2_f32_f16 v189, v174, v59, v189
	v_dot2_f32_f16 v188, v177, v60, v188
	v_dot2_f32_f16 v189, v161, v60, v189
	v_dot2_f32_f16 v188, v176, v61, v188
	v_dot2_f32_f16 v189, v160, v61, v189
	ds_read_b128 v[58:61], v183 offset:16896
	v_add_f32_dpp v186, v186, v186 quad_perm:[1,0,3,2] row_mask:0xf bank_mask:0xf bound_ctrl:1
	v_add_f32_dpp v187, v187, v187 quad_perm:[1,0,3,2] row_mask:0xf bank_mask:0xf bound_ctrl:1
	v_add_f32_dpp v188, v188, v188 quad_perm:[1,0,3,2] row_mask:0xf bank_mask:0xf bound_ctrl:1
	v_add_f32_dpp v189, v189, v189 quad_perm:[1,0,3,2] row_mask:0xf bank_mask:0xf bound_ctrl:1
	v_pk_mul_f16 v190, v185, v90
	v_pk_mul_f16 v191, v185, v91
	v_pk_mul_f16 v192, v185, v92
	v_pk_mul_f16 v193, v185, v93
	v_add_f32_dpp v186, v186, v186 quad_perm:[2,3,0,1] row_mask:0xf bank_mask:0xf bound_ctrl:1
	v_add_f32_dpp v187, v187, v187 quad_perm:[2,3,0,1] row_mask:0xf bank_mask:0xf bound_ctrl:1
	v_add_f32_dpp v188, v188, v188 quad_perm:[2,3,0,1] row_mask:0xf bank_mask:0xf bound_ctrl:1
	v_add_f32_dpp v189, v189, v189 quad_perm:[2,3,0,1] row_mask:0xf bank_mask:0xf bound_ctrl:1
	v_pk_fma_f16 v113, v113, v82, v190
	v_pk_fma_f16 v178, v178, v83, v191
	v_pk_fma_f16 v177, v177, v84, v192
	v_pk_fma_f16 v176, v176, v85, v193
	v_pk_mul_f16 v175, v175, v82
	v_pk_mul_f16 v174, v174, v83
	v_pk_mul_f16 v161, v161, v84
	v_pk_mul_f16 v160, v160, v85
	v_add_f32_dpp v186, v186, v186 row_half_mirror row_mask:0xf bank_mask:0xf bound_ctrl:1
	v_add_f32_dpp v187, v187, v187 row_half_mirror row_mask:0xf bank_mask:0xf bound_ctrl:1
	v_add_f32_dpp v188, v188, v188 row_half_mirror row_mask:0xf bank_mask:0xf bound_ctrl:1
	v_add_f32_dpp v189, v189, v189 row_half_mirror row_mask:0xf bank_mask:0xf bound_ctrl:1
	v_cvt_pk_f16_f32 v186, v186, v187
	v_pk_fma_f16 v113, v186, v86, v113 op_sel_hi:[0,1,1]
	v_pk_fma_f16 v175, v186, v86, v175 op_sel:[1,0,0] op_sel_hi:[1,1,1]
	v_pk_fma_f16 v178, v186, v87, v178 op_sel_hi:[0,1,1]
	v_pk_fma_f16 v174, v186, v87, v174 op_sel:[1,0,0] op_sel_hi:[1,1,1]
	v_pk_fma_f16 v177, v186, v88, v177 op_sel_hi:[0,1,1]
	v_pk_fma_f16 v161, v186, v88, v161 op_sel:[1,0,0] op_sel_hi:[1,1,1]
	v_pk_fma_f16 v176, v186, v89, v176 op_sel_hi:[0,1,1]
	v_pk_fma_f16 v160, v186, v89, v160 op_sel:[1,0,0] op_sel_hi:[1,1,1]
	s_and_saveexec_b64 s[30:31], s[2:3]
	ds_write2st64_b32 v182, v189, v188 offset0:114 offset1:146
	s_or_b64 exec, exec, s[30:31]
	s_waitcnt lgkmcnt(1)
	ds_read_b128 v[94:97], v183 offset:640
	ds_read_b128 v[86:89], v183 offset:4736
	ds_read_b128 v[82:85], v183 offset:8832
	ds_read_b128 v[90:93], v183 offset:12928
	ds_read_b32 v185, v182 offset:21760
	v_dot2_f32_f16 v186, v113, v74, 0
	v_dot2_f32_f16 v187, v175, v74, 0
	v_dot2_f32_f16 v186, v178, v75, v186
	v_dot2_f32_f16 v187, v174, v75, v187
	v_dot2_f32_f16 v186, v177, v76, v186
	v_dot2_f32_f16 v187, v161, v76, v187
	v_dot2_f32_f16 v186, v176, v77, v186
	v_dot2_f32_f16 v187, v160, v77, v187
	v_dot2_f32_f16 v188, v113, v78, 0
	v_dot2_f32_f16 v189, v175, v78, 0
	v_dot2_f32_f16 v188, v178, v79, v188
	v_dot2_f32_f16 v189, v174, v79, v189
	v_dot2_f32_f16 v188, v177, v80, v188
	v_dot2_f32_f16 v189, v161, v80, v189
	v_dot2_f32_f16 v188, v176, v81, v188
	v_dot2_f32_f16 v189, v160, v81, v189
	ds_read_b128 v[78:81], v183 offset:17024
	v_add_f32_dpp v186, v186, v186 quad_perm:[1,0,3,2] row_mask:0xf bank_mask:0xf bound_ctrl:1
	v_add_f32_dpp v187, v187, v187 quad_perm:[1,0,3,2] row_mask:0xf bank_mask:0xf bound_ctrl:1
	v_add_f32_dpp v188, v188, v188 quad_perm:[1,0,3,2] row_mask:0xf bank_mask:0xf bound_ctrl:1
	v_add_f32_dpp v189, v189, v189 quad_perm:[1,0,3,2] row_mask:0xf bank_mask:0xf bound_ctrl:1
	v_pk_mul_f16 v190, v184, v70
	v_pk_mul_f16 v191, v184, v71
	v_pk_mul_f16 v192, v184, v72
	v_pk_mul_f16 v193, v184, v73
	v_add_f32_dpp v186, v186, v186 quad_perm:[2,3,0,1] row_mask:0xf bank_mask:0xf bound_ctrl:1
	v_add_f32_dpp v187, v187, v187 quad_perm:[2,3,0,1] row_mask:0xf bank_mask:0xf bound_ctrl:1
	v_add_f32_dpp v188, v188, v188 quad_perm:[2,3,0,1] row_mask:0xf bank_mask:0xf bound_ctrl:1
	v_add_f32_dpp v189, v189, v189 quad_perm:[2,3,0,1] row_mask:0xf bank_mask:0xf bound_ctrl:1
	v_pk_fma_f16 v113, v113, v62, v190
	v_pk_fma_f16 v178, v178, v63, v191
	v_pk_fma_f16 v177, v177, v64, v192
	v_pk_fma_f16 v176, v176, v65, v193
	v_pk_mul_f16 v175, v175, v62
	v_pk_mul_f16 v174, v174, v63
	v_pk_mul_f16 v161, v161, v64
	v_pk_mul_f16 v160, v160, v65
	v_add_f32_dpp v186, v186, v186 row_half_mirror row_mask:0xf bank_mask:0xf bound_ctrl:1
	v_add_f32_dpp v187, v187, v187 row_half_mirror row_mask:0xf bank_mask:0xf bound_ctrl:1
	v_add_f32_dpp v188, v188, v188 row_half_mirror row_mask:0xf bank_mask:0xf bound_ctrl:1
	v_add_f32_dpp v189, v189, v189 row_half_mirror row_mask:0xf bank_mask:0xf bound_ctrl:1
	v_cvt_pk_f16_f32 v186, v186, v187
	v_pk_fma_f16 v113, v186, v66, v113 op_sel_hi:[0,1,1]
	v_pk_fma_f16 v175, v186, v66, v175 op_sel:[1,0,0] op_sel_hi:[1,1,1]
	v_pk_fma_f16 v178, v186, v67, v178 op_sel_hi:[0,1,1]
	v_pk_fma_f16 v174, v186, v67, v174 op_sel:[1,0,0] op_sel_hi:[1,1,1]
	v_pk_fma_f16 v177, v186, v68, v177 op_sel_hi:[0,1,1]
	v_pk_fma_f16 v161, v186, v68, v161 op_sel:[1,0,0] op_sel_hi:[1,1,1]
	v_pk_fma_f16 v176, v186, v69, v176 op_sel_hi:[0,1,1]
	v_pk_fma_f16 v160, v186, v69, v160 op_sel:[1,0,0] op_sel_hi:[1,1,1]
	s_and_saveexec_b64 s[30:31], s[2:3]
	ds_write2st64_b32 v182, v189, v188 offset0:115 offset1:147
	s_or_b64 exec, exec, s[30:31]
	s_add_i32 s37, s37, 1
	v_add_u32_e32 v183, 0x200, v183
	v_add_u32_e32 v182, 0x400, v182
	s_cmp_lg_u32 s37, 7
	s_cbranch_scc1 .Lscan_loop
	s_waitcnt lgkmcnt(1)
	ds_read_b128 v[74:77], v183 offset:256
	ds_read_b128 v[66:69], v183 offset:4352
	ds_read_b128 v[62:65], v183 offset:8448
	ds_read_b128 v[70:73], v183 offset:12544
	ds_read_b32 v184, v182 offset:20992
	v_dot2_f32_f16 v186, v113, v94, 0
	v_dot2_f32_f16 v187, v175, v94, 0
	v_dot2_f32_f16 v186, v178, v95, v186
	v_dot2_f32_f16 v187, v174, v95, v187
	v_dot2_f32_f16 v186, v177, v96, v186
	v_dot2_f32_f16 v187, v161, v96, v187
	v_dot2_f32_f16 v186, v176, v97, v186
	v_dot2_f32_f16 v187, v160, v97, v187
	v_dot2_f32_f16 v188, v113, v58, 0
	v_dot2_f32_f16 v189, v175, v58, 0
	v_dot2_f32_f16 v188, v178, v59, v188
	v_dot2_f32_f16 v189, v174, v59, v189
	v_dot2_f32_f16 v188, v177, v60, v188
	v_dot2_f32_f16 v189, v161, v60, v189
	v_dot2_f32_f16 v188, v176, v61, v188
	v_dot2_f32_f16 v189, v160, v61, v189
	ds_read_b128 v[58:61], v183 offset:16640
	v_add_f32_dpp v186, v186, v186 quad_perm:[1,0,3,2] row_mask:0xf bank_mask:0xf bound_ctrl:1
	v_add_f32_dpp v187, v187, v187 quad_perm:[1,0,3,2] row_mask:0xf bank_mask:0xf bound_ctrl:1
	v_add_f32_dpp v188, v188, v188 quad_perm:[1,0,3,2] row_mask:0xf bank_mask:0xf bound_ctrl:1
	v_add_f32_dpp v189, v189, v189 quad_perm:[1,0,3,2] row_mask:0xf bank_mask:0xf bound_ctrl:1
	v_pk_mul_f16 v190, v185, v90
	v_pk_mul_f16 v191, v185, v91
	v_pk_mul_f16 v192, v185, v92
	v_pk_mul_f16 v193, v185, v93
	v_add_f32_dpp v186, v186, v186 quad_perm:[2,3,0,1] row_mask:0xf bank_mask:0xf bound_ctrl:1
	v_add_f32_dpp v187, v187, v187 quad_perm:[2,3,0,1] row_mask:0xf bank_mask:0xf bound_ctrl:1
	v_add_f32_dpp v188, v188, v188 quad_perm:[2,3,0,1] row_mask:0xf bank_mask:0xf bound_ctrl:1
	v_add_f32_dpp v189, v189, v189 quad_perm:[2,3,0,1] row_mask:0xf bank_mask:0xf bound_ctrl:1
	v_pk_fma_f16 v113, v113, v82, v190
	v_pk_fma_f16 v178, v178, v83, v191
	v_pk_fma_f16 v177, v177, v84, v192
	v_pk_fma_f16 v176, v176, v85, v193
	v_pk_mul_f16 v175, v175, v82
	v_pk_mul_f16 v174, v174, v83
	v_pk_mul_f16 v161, v161, v84
	v_pk_mul_f16 v160, v160, v85
	v_add_f32_dpp v186, v186, v186 row_half_mirror row_mask:0xf bank_mask:0xf bound_ctrl:1
	v_add_f32_dpp v187, v187, v187 row_half_mirror row_mask:0xf bank_mask:0xf bound_ctrl:1
	v_add_f32_dpp v188, v188, v188 row_half_mirror row_mask:0xf bank_mask:0xf bound_ctrl:1
	v_add_f32_dpp v189, v189, v189 row_half_mirror row_mask:0xf bank_mask:0xf bound_ctrl:1
	v_cvt_pk_f16_f32 v186, v186, v187
	v_pk_fma_f16 v113, v186, v86, v113 op_sel_hi:[0,1,1]
	v_pk_fma_f16 v175, v186, v86, v175 op_sel:[1,0,0] op_sel_hi:[1,1,1]
	v_pk_fma_f16 v178, v186, v87, v178 op_sel_hi:[0,1,1]
	v_pk_fma_f16 v174, v186, v87, v174 op_sel:[1,0,0] op_sel_hi:[1,1,1]
	v_pk_fma_f16 v177, v186, v88, v177 op_sel_hi:[0,1,1]
	v_pk_fma_f16 v161, v186, v88, v161 op_sel:[1,0,0] op_sel_hi:[1,1,1]
	v_pk_fma_f16 v176, v186, v89, v176 op_sel_hi:[0,1,1]
	v_pk_fma_f16 v160, v186, v89, v160 op_sel:[1,0,0] op_sel_hi:[1,1,1]
	s_and_saveexec_b64 s[30:31], s[2:3]
	ds_write2st64_b32 v182, v189, v188 offset0:112 offset1:144
	s_or_b64 exec, exec, s[30:31]
	s_waitcnt lgkmcnt(1)
	ds_read_b128 v[94:97], v183 offset:384
	ds_read_b128 v[86:89], v183 offset:4480
	ds_read_b128 v[82:85], v183 offset:8576
	ds_read_b128 v[90:93], v183 offset:12672
	ds_read_b32 v185, v182 offset:21248
	v_dot2_f32_f16 v186, v113, v74, 0
	v_dot2_f32_f16 v187, v175, v74, 0
	v_dot2_f32_f16 v186, v178, v75, v186
	v_dot2_f32_f16 v187, v174, v75, v187
	v_dot2_f32_f16 v186, v177, v76, v186
	v_dot2_f32_f16 v187, v161, v76, v187
	v_dot2_f32_f16 v186, v176, v77, v186
	v_dot2_f32_f16 v187, v160, v77, v187
	v_dot2_f32_f16 v188, v113, v78, 0
	v_dot2_f32_f16 v189, v175, v78, 0
	v_dot2_f32_f16 v188, v178, v79, v188
	v_dot2_f32_f16 v189, v174, v79, v189
	v_dot2_f32_f16 v188, v177, v80, v188
	v_dot2_f32_f16 v189, v161, v80, v189
	v_dot2_f32_f16 v188, v176, v81, v188
	v_dot2_f32_f16 v189, v160, v81, v189
	ds_read_b128 v[78:81], v183 offset:16768
	v_add_f32_dpp v186, v186, v186 quad_perm:[1,0,3,2] row_mask:0xf bank_mask:0xf bound_ctrl:1
	v_add_f32_dpp v187, v187, v187 quad_perm:[1,0,3,2] row_mask:0xf bank_mask:0xf bound_ctrl:1
	v_add_f32_dpp v188, v188, v188 quad_perm:[1,0,3,2] row_mask:0xf bank_mask:0xf bound_ctrl:1
	v_add_f32_dpp v189, v189, v189 quad_perm:[1,0,3,2] row_mask:0xf bank_mask:0xf bound_ctrl:1
	v_pk_mul_f16 v190, v184, v70
	v_pk_mul_f16 v191, v184, v71
	v_pk_mul_f16 v192, v184, v72
	v_pk_mul_f16 v193, v184, v73
	v_add_f32_dpp v186, v186, v186 quad_perm:[2,3,0,1] row_mask:0xf bank_mask:0xf bound_ctrl:1
	v_add_f32_dpp v187, v187, v187 quad_perm:[2,3,0,1] row_mask:0xf bank_mask:0xf bound_ctrl:1
	v_add_f32_dpp v188, v188, v188 quad_perm:[2,3,0,1] row_mask:0xf bank_mask:0xf bound_ctrl:1
	v_add_f32_dpp v189, v189, v189 quad_perm:[2,3,0,1] row_mask:0xf bank_mask:0xf bound_ctrl:1
	v_pk_fma_f16 v113, v113, v62, v190
	v_pk_fma_f16 v178, v178, v63, v191
	v_pk_fma_f16 v177, v177, v64, v192
	v_pk_fma_f16 v176, v176, v65, v193
	v_pk_mul_f16 v175, v175, v62
	v_pk_mul_f16 v174, v174, v63
	v_pk_mul_f16 v161, v161, v64
	v_pk_mul_f16 v160, v160, v65
	v_add_f32_dpp v186, v186, v186 row_half_mirror row_mask:0xf bank_mask:0xf bound_ctrl:1
	v_add_f32_dpp v187, v187, v187 row_half_mirror row_mask:0xf bank_mask:0xf bound_ctrl:1
	v_add_f32_dpp v188, v188, v188 row_half_mirror row_mask:0xf bank_mask:0xf bound_ctrl:1
	v_add_f32_dpp v189, v189, v189 row_half_mirror row_mask:0xf bank_mask:0xf bound_ctrl:1
	v_cvt_pk_f16_f32 v186, v186, v187
	v_pk_fma_f16 v113, v186, v66, v113 op_sel_hi:[0,1,1]
	v_pk_fma_f16 v175, v186, v66, v175 op_sel:[1,0,0] op_sel_hi:[1,1,1]
	v_pk_fma_f16 v178, v186, v67, v178 op_sel_hi:[0,1,1]
	v_pk_fma_f16 v174, v186, v67, v174 op_sel:[1,0,0] op_sel_hi:[1,1,1]
	v_pk_fma_f16 v177, v186, v68, v177 op_sel_hi:[0,1,1]
	v_pk_fma_f16 v161, v186, v68, v161 op_sel:[1,0,0] op_sel_hi:[1,1,1]
	v_pk_fma_f16 v176, v186, v69, v176 op_sel_hi:[0,1,1]
	v_pk_fma_f16 v160, v186, v69, v160 op_sel:[1,0,0] op_sel_hi:[1,1,1]
	s_and_saveexec_b64 s[30:31], s[2:3]
	ds_write2st64_b32 v182, v189, v188 offset0:113 offset1:145
	s_or_b64 exec, exec, s[30:31]
	s_waitcnt lgkmcnt(1)
	v_dot2_f32_f16 v186, v113, v94, 0
	v_dot2_f32_f16 v187, v175, v94, 0
	v_dot2_f32_f16 v186, v178, v95, v186
	v_dot2_f32_f16 v187, v174, v95, v187
	v_dot2_f32_f16 v186, v177, v96, v186
	v_dot2_f32_f16 v187, v161, v96, v187
	v_dot2_f32_f16 v186, v176, v97, v186
	v_dot2_f32_f16 v187, v160, v97, v187
	v_dot2_f32_f16 v188, v113, v58, 0
	v_dot2_f32_f16 v189, v175, v58, 0
	v_dot2_f32_f16 v188, v178, v59, v188
	v_dot2_f32_f16 v189, v174, v59, v189
	v_dot2_f32_f16 v188, v177, v60, v188
	v_dot2_f32_f16 v189, v161, v60, v189
	v_dot2_f32_f16 v188, v176, v61, v188
	v_dot2_f32_f16 v189, v160, v61, v189
	v_add_f32_dpp v186, v186, v186 quad_perm:[1,0,3,2] row_mask:0xf bank_mask:0xf bound_ctrl:1
	v_add_f32_dpp v187, v187, v187 quad_perm:[1,0,3,2] row_mask:0xf bank_mask:0xf bound_ctrl:1
	v_add_f32_dpp v188, v188, v188 quad_perm:[1,0,3,2] row_mask:0xf bank_mask:0xf bound_ctrl:1
	v_add_f32_dpp v189, v189, v189 quad_perm:[1,0,3,2] row_mask:0xf bank_mask:0xf bound_ctrl:1
	v_pk_mul_f16 v190, v185, v90
	v_pk_mul_f16 v191, v185, v91
	v_pk_mul_f16 v192, v185, v92
	v_pk_mul_f16 v193, v185, v93
	v_add_f32_dpp v186, v186, v186 quad_perm:[2,3,0,1] row_mask:0xf bank_mask:0xf bound_ctrl:1
	v_add_f32_dpp v187, v187, v187 quad_perm:[2,3,0,1] row_mask:0xf bank_mask:0xf bound_ctrl:1
	v_add_f32_dpp v188, v188, v188 quad_perm:[2,3,0,1] row_mask:0xf bank_mask:0xf bound_ctrl:1
	v_add_f32_dpp v189, v189, v189 quad_perm:[2,3,0,1] row_mask:0xf bank_mask:0xf bound_ctrl:1
	v_pk_fma_f16 v113, v113, v82, v190
	v_pk_fma_f16 v178, v178, v83, v191
	v_pk_fma_f16 v177, v177, v84, v192
	v_pk_fma_f16 v176, v176, v85, v193
	v_pk_mul_f16 v175, v175, v82
	v_pk_mul_f16 v174, v174, v83
	v_pk_mul_f16 v161, v161, v84
	v_pk_mul_f16 v160, v160, v85
	v_add_f32_dpp v186, v186, v186 row_half_mirror row_mask:0xf bank_mask:0xf bound_ctrl:1
	v_add_f32_dpp v187, v187, v187 row_half_mirror row_mask:0xf bank_mask:0xf bound_ctrl:1
	v_add_f32_dpp v188, v188, v188 row_half_mirror row_mask:0xf bank_mask:0xf bound_ctrl:1
	v_add_f32_dpp v189, v189, v189 row_half_mirror row_mask:0xf bank_mask:0xf bound_ctrl:1
	v_cvt_pk_f16_f32 v186, v186, v187
	v_pk_fma_f16 v113, v186, v86, v113 op_sel_hi:[0,1,1]
	v_pk_fma_f16 v175, v186, v86, v175 op_sel:[1,0,0] op_sel_hi:[1,1,1]
	v_pk_fma_f16 v178, v186, v87, v178 op_sel_hi:[0,1,1]
	v_pk_fma_f16 v174, v186, v87, v174 op_sel:[1,0,0] op_sel_hi:[1,1,1]
	v_pk_fma_f16 v177, v186, v88, v177 op_sel_hi:[0,1,1]
	v_pk_fma_f16 v161, v186, v88, v161 op_sel:[1,0,0] op_sel_hi:[1,1,1]
	v_pk_fma_f16 v176, v186, v89, v176 op_sel_hi:[0,1,1]
	v_pk_fma_f16 v160, v186, v89, v160 op_sel:[1,0,0] op_sel_hi:[1,1,1]
	s_and_saveexec_b64 s[30:31], s[2:3]
	ds_write2st64_b32 v182, v189, v188 offset0:114 offset1:146
	s_or_b64 exec, exec, s[30:31]
	s_waitcnt lgkmcnt(1)
	v_dot2_f32_f16 v188, v113, v78, 0
	v_dot2_f32_f16 v189, v175, v78, 0
	v_dot2_f32_f16 v188, v178, v79, v188
	v_dot2_f32_f16 v189, v174, v79, v189
	v_dot2_f32_f16 v188, v177, v80, v188
	v_dot2_f32_f16 v189, v161, v80, v189
	v_dot2_f32_f16 v188, v176, v81, v188
	v_dot2_f32_f16 v189, v160, v81, v189
	s_nop 2
	v_add_f32_dpp v188, v188, v188 quad_perm:[1,0,3,2] row_mask:0xf bank_mask:0xf bound_ctrl:1
	v_add_f32_dpp v189, v189, v189 quad_perm:[1,0,3,2] row_mask:0xf bank_mask:0xf bound_ctrl:1
	s_nop 0
	v_add_f32_dpp v188, v188, v188 quad_perm:[2,3,0,1] row_mask:0xf bank_mask:0xf bound_ctrl:1
	v_add_f32_dpp v189, v189, v189 quad_perm:[2,3,0,1] row_mask:0xf bank_mask:0xf bound_ctrl:1
	s_nop 0
	v_add_f32_dpp v188, v188, v188 row_half_mirror row_mask:0xf bank_mask:0xf bound_ctrl:1
	v_add_f32_dpp v189, v189, v189 row_half_mirror row_mask:0xf bank_mask:0xf bound_ctrl:1
	s_and_saveexec_b64 s[30:31], s[2:3]
	ds_write2st64_b32 v182, v189, v188 offset0:115 offset1:147
	s_or_b64 exec, exec, s[30:31]

; __device__ __forceinline__ unsigned pk2(float lo, float hi) { unsigned r; asm("v_cvt_pk_bf16_f32 %0, %1, %2" : "=v"(r) : "v"(lo), "v"(hi)); return r; }
;     __device__ __forceinline__ void operator()(const pg8::f32x4 (&acc)[2][2][4][2], const pg8::Unit& u, int wr, int wc, int fr, int fq) const {
;         const int col0 = u.pn * 256 + wc * 32 + 8 * fq;
;         f32x4 bv[2][2];
; #pragma unroll
;         for (int bj = 0; bj < 2; ++bj)
; #pragma unroll
;             for (int n = 0; n < 2; ++n) bv[bj][n] = bias ? *(const f32x4*)(bias + col0 + bj * 128 + 4 * n) : (f32x4){0.f, 0.f, 0.f, 0.f};
; #pragma unroll
;         for (int ai = 0; ai < 2; ++ai)
; #pragma unroll
;             for (int m = 0; m < 4; ++m) { const int r = u.pm * 256 + ai * 128 + wr * 64 + m * 16 + fr; bf16* rowp = RB + (size_t)r * ldc + col0;
;                 float ss = 0.f;
; #pragma unroll
;                 for (int bj = 0; bj < 2; ++bj) { const u32x4 old = *(const u32x4*)(rowp + bj * 128); u32x4 w;
; #pragma unroll
;                     for (int x = 0; x < 4; ++x) { const int n = x >> 1, e = (x & 1) * 2;
;                         const float lo = __uint_as_float(old[x] << 16) + acc[ai][bj][m][n][e] + bv[bj][n][e], hi = __uint_as_float(old[x] & 0xffff0000u) + acc[ai][bj][m][n][e + 1] + bv[bj][n][e + 1];
;                         const unsigned pw = pk2(lo, hi); w[x] = pw;
;                         const float rl = __uint_as_float(pw << 16), rh = __uint_as_float(pw & 0xffff0000u); ss += rl * rl + rh * rh; }
;                     *(u32x4*)(rowp + bj * 128) = w; }
;                 ss += __shfl_xor(ss, 16); ss += __shfl_xor(ss, 32);
;                 if (fq == 0) ssq[(size_t)r * 16 + u.pn * 4 + wc] = ss; }
;     }
.LBB0_757:
	v_lshl_add_u32 v160, s61, 8, v147
	v_ashrrev_i32_e32 v161, 31, v160
	v_lshlrev_b64 v[178:179], 11, v[160:161]
	v_lshl_add_u64 v[178:179], s[16:17], 0, v[178:179]
	v_lshl_add_u64 v[186:187], v[158:159], 1, v[178:179]
	global_load_dwordx4 v[178:181], v[186:187], off
	global_load_dwordx4 v[182:185], v[186:187], off offset:256
	s_mov_b32 s29, 0
	s_mov_b32 s28, 0x8000
	v_lshl_add_u64 v[196:197], v[186:187], 0, s[28:29]
	global_load_dwordx4 v[204:207], v[196:197], off
	global_load_dwordx4 v[208:211], v[196:197], off offset:256
	s_mov_b32 s28, 0x10000
	v_lshl_add_u64 v[198:199], v[186:187], 0, s[28:29]
	global_load_dwordx4 v[212:215], v[198:199], off
	global_load_dwordx4 v[216:219], v[198:199], off offset:256
	s_mov_b32 s28, 0x18000
	v_lshl_add_u64 v[200:201], v[186:187], 0, s[28:29]
	global_load_dwordx4 v[220:223], v[200:201], off
	global_load_dwordx4 v[224:227], v[200:201], off offset:256
	s_mov_b32 s28, 0x40000
	v_lshl_add_u64 v[202:203], v[186:187], 0, s[28:29]
	global_load_dwordx4 v[228:231], v[202:203], off
	global_load_dwordx4 v[232:235], v[202:203], off offset:256
	s_mov_b32 s28, 0x48000
	v_lshl_add_u64 v[196:197], v[186:187], 0, s[28:29]
	s_mov_b32 s28, 0x50000
	v_lshl_add_u64 v[198:199], v[186:187], 0, s[28:29]
	s_mov_b32 s28, 0x58000
	v_lshl_add_u64 v[200:201], v[186:187], 0, s[28:29]
	s_lshl_b32 s0, s60, 2
	s_ashr_i32 s1, s0, 31
	s_waitcnt vmcnt(8)
	v_lshlrev_b32_e32 v177, 16, v178
	v_and_b32_e32 v178, 0xffff0000, v178
	v_lshlrev_b32_e32 v193, 16, v184
	v_and_b32_e32 v184, 0xffff0000, v184
	v_lshlrev_b32_e32 v194, 16, v185
	v_and_b32_e32 v185, 0xffff0000, v185
	v_lshlrev_b32_e32 v188, 16, v179
	v_and_b32_e32 v179, 0xffff0000, v179
	v_lshlrev_b32_e32 v189, 16, v180
	v_and_b32_e32 v180, 0xffff0000, v180
	v_lshlrev_b32_e32 v190, 16, v181
	v_lshlrev_b32_e32 v191, 16, v182
	v_and_b32_e32 v182, 0xffff0000, v182
	v_lshlrev_b32_e32 v192, 16, v183
	v_and_b32_e32 v183, 0xffff0000, v183
	v_add_f32_e32 v142, v142, v177
	v_add_f32_e32 v143, v143, v178
	v_add_f32_e32 v131, v131, v184
	v_add_f32_e32 v133, v133, v185
	v_and_b32_e32 v181, 0xffff0000, v181
	v_add_f32_e32 v144, v144, v188
	v_add_f32_e32 v145, v145, v179
	v_add_f32_e32 v138, v138, v189
	v_add_f32_e32 v139, v139, v180
	v_add_f32_e32 v140, v140, v190
	v_add_f32_e32 v135, v135, v182
	v_add_f32_e32 v136, v136, v192
	v_add_f32_e32 v137, v137, v183
	v_add_f32_e32 v130, v130, v193
	v_add_f32_e32 v132, v132, v194
	v_add_f32_e32 v142, v50, v142
	v_add_f32_e32 v143, v51, v143
	v_add_f32_e32 v131, v27, v131
	v_add_f32_e32 v133, v29, v133
	v_add_f32_e32 v141, v141, v181
	v_add_f32_e32 v134, v134, v191
	v_add_f32_e32 v144, v52, v144
	v_add_f32_e32 v145, v53, v145
	v_add_f32_e32 v138, v42, v138
	v_add_f32_e32 v139, v43, v139
	v_add_f32_e32 v140, v44, v140
	v_add_f32_e32 v135, v39, v135
	v_add_f32_e32 v177, v40, v136
	v_add_f32_e32 v178, v41, v137
	v_add_f32_e32 v130, v26, v130
	v_add_f32_e32 v132, v28, v132
	v_cvt_pk_bf16_f32 v136, v142, v143
	v_cvt_pk_bf16_f32 v137, v144, v145
	v_cvt_pk_bf16_f32 v142, v130, v131
	v_cvt_pk_bf16_f32 v143, v132, v133
	v_add_f32_e32 v141, v45, v141
	v_and_b32_e32 v131, 0xffff0000, v136
	v_and_b32_e32 v133, 0xffff0000, v137
	v_add_f32_e32 v134, v38, v134
	v_cvt_pk_bf16_f32 v138, v138, v139
	v_cvt_pk_bf16_f32 v139, v140, v141
	v_cvt_pk_bf16_f32 v140, v134, v135
	v_lshlrev_b32_e32 v130, 16, v136
	v_lshlrev_b32_e32 v132, 16, v137
	v_and_b32_e32 v135, 0xffff0000, v138
	v_mul_f32_e32 v131, v131, v131
	v_mul_f32_e32 v133, v133, v133
	v_lshlrev_b32_e32 v134, 16, v138
	v_and_b32_e32 v145, 0xffff0000, v139
	v_mul_f32_e32 v135, v135, v135
	v_fmac_f32_e32 v131, v130, v130
	v_fmac_f32_e32 v133, v132, v132
	v_cvt_pk_bf16_f32 v141, v177, v178
	v_lshlrev_b32_e32 v144, 16, v139
	v_and_b32_e32 v178, 0xffff0000, v140
	v_mul_f32_e32 v145, v145, v145
	v_fmac_f32_e32 v135, v134, v134
	v_add_f32_e32 v130, v131, v133
	v_lshlrev_b32_e32 v177, 16, v140
	v_and_b32_e32 v180, 0xffff0000, v141
	v_mul_f32_e32 v178, v178, v178
	v_fmac_f32_e32 v145, v144, v144
	v_add_f32_e32 v130, v130, v135
	v_lshlrev_b32_e32 v179, 16, v141
	v_and_b32_e32 v182, 0xffff0000, v142
	v_mul_f32_e32 v180, v180, v180
	v_fmac_f32_e32 v178, v177, v177
	v_add_f32_e32 v130, v130, v145
	v_lshlrev_b32_e32 v181, 16, v142
	v_mul_f32_e32 v182, v182, v182
	v_fmac_f32_e32 v180, v179, v179
	v_add_f32_e32 v130, v130, v178
	v_and_b32_e32 v131, 0xffff0000, v143
	v_lshlrev_b32_e32 v183, 16, v143
	v_fmac_f32_e32 v182, v181, v181
	v_add_f32_e32 v130, v130, v180
	v_mul_f32_e32 v131, v131, v131
	v_add_f32_e32 v130, v130, v182
	v_fmac_f32_e32 v131, v183, v183
	v_and_b32_e32 v132, 64, v163
	v_add_f32_e32 v130, v130, v131
	v_xor_b32_e32 v131, 16, v163
	v_add_u32_e32 v132, 64, v132
	v_cmp_lt_i32_e32 vcc, v131, v132
	global_store_dwordx4 v[186:187], v[136:139], off
	global_store_dwordx4 v[186:187], v[140:143], off offset:256
	v_cndmask_b32_e32 v131, v163, v131, vcc
	v_lshlrev_b32_e32 v134, 2, v131
	ds_bpermute_b32 v131, v134, v130
	s_waitcnt lgkmcnt(0)
	v_add_f32_e32 v130, v130, v131
	v_xor_b32_e32 v131, 32, v163
	v_cmp_lt_i32_e32 vcc, v131, v132
	s_nop 1
	v_cndmask_b32_e32 v131, v163, v131, vcc
	v_lshlrev_b32_e32 v135, 2, v131
	ds_bpermute_b32 v131, v135, v130
	s_and_saveexec_b64 s[28:29], s[38:39]
	s_cbranch_execz .LBB0_759
	s_waitcnt lgkmcnt(0)
	v_add_f32_e32 v132, v130, v131
	v_lshlrev_b64 v[130:131], 6, v[160:161]
	v_lshl_add_u64 v[130:131], s[14:15], 0, v[130:131]
	v_lshl_add_u64 v[130:131], s[0:1], 2, v[130:131]
	s_mov_b32 s61, s89
	s_lshl_b32 s60, s46, 2
	v_lshl_add_u64 v[130:131], v[130:131], 0, s[60:61]
	global_store_dword v[130:131], v132, off
; __device__ __forceinline__ unsigned pk2(float lo, float hi) { unsigned r; asm("v_cvt_pk_bf16_f32 %0, %1, %2" : "=v"(r) : "v"(lo), "v"(hi)); return r; }
;     __device__ __forceinline__ void operator()(const pg8::f32x4 (&acc)[2][2][4][2], const pg8::Unit& u, int wr, int wc, int fr, int fq) const {
;     ...
;             for (int m = 0; m < 4; ++m) { const int r = u.pm * 256 + ai * 128 + wr * 64 + m * 16 + fr; bf16* rowp = RB + (size_t)r * ldc + col0;
;                 float ss = 0.f;
; #pragma unroll
;                 for (int bj = 0; bj < 2; ++bj) { const u32x4 old = *(const u32x4*)(rowp + bj * 128); u32x4 w;
; #pragma unroll
;                     for (int x = 0; x < 4; ++x) { const int n = x >> 1, e = (x & 1) * 2;
;                         const float lo = __uint_as_float(old[x] << 16) + acc[ai][bj][m][n][e] + bv[bj][n][e], hi = __uint_as_float(old[x] & 0xffff0000u) + acc[ai][bj][m][n][e + 1] + bv[bj][n][e + 1];
;                         const unsigned pw = pk2(lo, hi); w[x] = pw;
;                         const float rl = __uint_as_float(pw << 16), rh = __uint_as_float(pw & 0xffff0000u); ss += rl * rl + rh * rh; }
;                     *(u32x4*)(rowp + bj * 128) = w; }
;                 ss += __shfl_xor(ss, 16); ss += __shfl_xor(ss, 32);
;                 if (fq == 0) ssq[(size_t)r * 16 + u.pn * 4 + wc] = ss; }
.LBB0_759:
	s_or_b64 exec, exec, s[28:29]
	v_or_b32_e32 v130, 16, v160
	s_waitcnt lgkmcnt(0)
	v_ashrrev_i32_e32 v131, 31, v130
	v_lshlrev_b64 v[132:133], 11, v[130:131]
	v_lshl_add_u64 v[132:133], s[16:17], 0, v[132:133]
	v_lshl_add_u64 v[132:133], v[158:159], 1, v[132:133]
	s_waitcnt vmcnt(9)
	v_mov_b64_e32 v[136:137], v[204:205]
	v_mov_b64_e32 v[138:139], v[206:207]
	global_load_dwordx4 v[204:207], v[196:197], off
	v_lshlrev_b32_e32 v140, 16, v136
	v_add_f32_e32 v126, v126, v140
	v_and_b32_e32 v136, 0xffff0000, v136
	v_add_f32_e32 v126, v50, v126
	v_add_f32_e32 v127, v127, v136
	v_add_f32_e32 v127, v51, v127
	v_cvt_pk_bf16_f32 v126, v126, v127
	s_nop 0
	v_and_b32_e32 v136, 0xffff0000, v126
	v_lshlrev_b32_e32 v127, 16, v126
	v_mul_f32_e32 v136, v136, v136
	v_fmac_f32_e32 v136, v127, v127
	v_lshlrev_b32_e32 v127, 16, v137
	v_add_f32_e32 v127, v128, v127
	v_and_b32_e32 v128, 0xffff0000, v137
	v_add_f32_e32 v127, v52, v127
	v_add_f32_e32 v128, v129, v128
	v_add_f32_e32 v128, v53, v128
	v_cvt_pk_bf16_f32 v127, v127, v128
	s_nop 0
	v_and_b32_e32 v129, 0xffff0000, v127
	v_lshlrev_b32_e32 v128, 16, v127
	v_mul_f32_e32 v129, v129, v129
	v_fmac_f32_e32 v129, v128, v128
	v_lshlrev_b32_e32 v128, 16, v138
	v_add_f32_e32 v122, v122, v128
	v_and_b32_e32 v128, 0xffff0000, v138
	v_add_f32_e32 v123, v123, v128
	v_add_f32_e32 v123, v43, v123
	v_add_f32_e32 v122, v42, v122
	v_cvt_pk_bf16_f32 v128, v122, v123
	v_add_f32_e32 v129, v136, v129
	v_and_b32_e32 v123, 0xffff0000, v128
	v_lshlrev_b32_e32 v122, 16, v128
	v_mul_f32_e32 v123, v123, v123
	v_fmac_f32_e32 v123, v122, v122
	v_add_f32_e32 v122, v129, v123
	v_lshlrev_b32_e32 v123, 16, v139
	v_add_f32_e32 v123, v124, v123
	v_and_b32_e32 v124, 0xffff0000, v139
	v_add_f32_e32 v124, v125, v124
	v_add_f32_e32 v124, v45, v124
	v_add_f32_e32 v123, v44, v123
	v_cvt_pk_bf16_f32 v129, v123, v124
	global_store_dwordx4 v[132:133], v[126:129], off
	v_and_b32_e32 v124, 0xffff0000, v129
	v_lshlrev_b32_e32 v123, 16, v129
	v_mul_f32_e32 v124, v124, v124
	v_fmac_f32_e32 v124, v123, v123
	v_add_f32_e32 v136, v122, v124
	s_waitcnt vmcnt(10)
	v_mov_b64_e32 v[122:123], v[208:209]
	v_mov_b64_e32 v[124:125], v[210:211]
	global_load_dwordx4 v[208:211], v[196:197], off offset:256
	v_lshlrev_b32_e32 v126, 16, v122
	v_add_f32_e32 v118, v118, v126
	v_and_b32_e32 v122, 0xffff0000, v122
	v_add_f32_e32 v118, v38, v118
	v_add_f32_e32 v119, v119, v122
	v_add_f32_e32 v119, v39, v119
	v_cvt_pk_bf16_f32 v118, v118, v119
	s_nop 0
	v_and_b32_e32 v122, 0xffff0000, v118
	v_lshlrev_b32_e32 v119, 16, v118
	v_mul_f32_e32 v122, v122, v122
	v_fmac_f32_e32 v122, v119, v119
	v_lshlrev_b32_e32 v119, 16, v123
	v_add_f32_e32 v119, v120, v119
	v_and_b32_e32 v120, 0xffff0000, v123
	v_add_f32_e32 v119, v40, v119
	v_add_f32_e32 v120, v121, v120
	v_add_f32_e32 v120, v41, v120
	v_cvt_pk_bf16_f32 v119, v119, v120
	v_add_f32_e32 v122, v136, v122
	v_and_b32_e32 v121, 0xffff0000, v119
	v_lshlrev_b32_e32 v120, 16, v119
	v_mul_f32_e32 v121, v121, v121
	v_fmac_f32_e32 v121, v120, v120
	v_lshlrev_b32_e32 v120, 16, v124
	v_add_f32_e32 v114, v114, v120
	v_and_b32_e32 v120, 0xffff0000, v124
	v_add_f32_e32 v115, v115, v120
	v_add_f32_e32 v115, v27, v115
	v_add_f32_e32 v114, v26, v114
	v_cvt_pk_bf16_f32 v120, v114, v115
	v_add_f32_e32 v121, v122, v121
	v_and_b32_e32 v115, 0xffff0000, v120
	v_lshlrev_b32_e32 v114, 16, v120
	v_mul_f32_e32 v115, v115, v115
	v_fmac_f32_e32 v115, v114, v114
	v_add_f32_e32 v114, v121, v115
	v_lshlrev_b32_e32 v115, 16, v125
	v_add_f32_e32 v115, v116, v115
	v_and_b32_e32 v116, 0xffff0000, v125
	v_add_f32_e32 v116, v117, v116
	v_add_f32_e32 v116, v29, v116
	v_add_f32_e32 v115, v28, v115
	v_cvt_pk_bf16_f32 v121, v115, v116
	global_store_dwordx4 v[132:133], v[118:121], off offset:256
	v_and_b32_e32 v116, 0xffff0000, v121
	v_lshlrev_b32_e32 v115, 16, v121
	v_mul_f32_e32 v116, v116, v116
	v_fmac_f32_e32 v116, v115, v115
	v_add_f32_e32 v114, v114, v116
	ds_bpermute_b32 v115, v134, v114
	s_waitcnt lgkmcnt(0)
	v_add_f32_e32 v114, v114, v115
	ds_bpermute_b32 v115, v135, v114
	s_and_saveexec_b64 s[28:29], s[38:39]
	s_cbranch_execz .LBB0_761
	s_waitcnt lgkmcnt(0)
	v_add_f32_e32 v116, v114, v115
	v_lshlrev_b64 v[114:115], 6, v[130:131]
	v_lshl_add_u64 v[114:115], s[14:15], 0, v[114:115]
	v_lshl_add_u64 v[114:115], s[0:1], 2, v[114:115]
	s_mov_b32 s61, s89
	s_lshl_b32 s60, s46, 2
	v_lshl_add_u64 v[114:115], v[114:115], 0, s[60:61]
	global_store_dword v[114:115], v116, off
; __device__ __forceinline__ unsigned pk2(float lo, float hi) { unsigned r; asm("v_cvt_pk_bf16_f32 %0, %1, %2" : "=v"(r) : "v"(lo), "v"(hi)); return r; }
;     __device__ __forceinline__ void operator()(const pg8::f32x4 (&acc)[2][2][4][2], const pg8::Unit& u, int wr, int wc, int fr, int fq) const {
;     ...
;             for (int m = 0; m < 4; ++m) { const int r = u.pm * 256 + ai * 128 + wr * 64 + m * 16 + fr; bf16* rowp = RB + (size_t)r * ldc + col0;
;                 float ss = 0.f;
; #pragma unroll
;                 for (int bj = 0; bj < 2; ++bj) { const u32x4 old = *(const u32x4*)(rowp + bj * 128); u32x4 w;
; #pragma unroll
;                     for (int x = 0; x < 4; ++x) { const int n = x >> 1, e = (x & 1) * 2;
;                         const float lo = __uint_as_float(old[x] << 16) + acc[ai][bj][m][n][e] + bv[bj][n][e], hi = __uint_as_float(old[x] & 0xffff0000u) + acc[ai][bj][m][n][e + 1] + bv[bj][n][e + 1];
;                         const unsigned pw = pk2(lo, hi); w[x] = pw;
;                         const float rl = __uint_as_float(pw << 16), rh = __uint_as_float(pw & 0xffff0000u); ss += rl * rl + rh * rh; }
;                     *(u32x4*)(rowp + bj * 128) = w; }
;                 ss += __shfl_xor(ss, 16); ss += __shfl_xor(ss, 32);
;                 if (fq == 0) ssq[(size_t)r * 16 + u.pn * 4 + wc] = ss; }
.LBB0_761:
	s_or_b64 exec, exec, s[28:29]
	v_or_b32_e32 v114, 32, v160
	s_waitcnt lgkmcnt(0)
	v_ashrrev_i32_e32 v115, 31, v114
	v_lshlrev_b64 v[116:117], 11, v[114:115]
	v_lshl_add_u64 v[116:117], s[16:17], 0, v[116:117]
	v_lshl_add_u64 v[116:117], v[158:159], 1, v[116:117]
	s_waitcnt vmcnt(11)
	v_mov_b64_e32 v[118:119], v[212:213]
	v_mov_b64_e32 v[120:121], v[214:215]
	global_load_dwordx4 v[212:215], v[198:199], off
	v_lshlrev_b32_e32 v122, 16, v118
	v_add_f32_e32 v110, v110, v122
	v_and_b32_e32 v118, 0xffff0000, v118
	v_add_f32_e32 v110, v50, v110
	v_add_f32_e32 v111, v111, v118
	v_add_f32_e32 v111, v51, v111
	v_cvt_pk_bf16_f32 v110, v110, v111
	s_nop 0
	v_and_b32_e32 v118, 0xffff0000, v110
	v_lshlrev_b32_e32 v111, 16, v110
	v_mul_f32_e32 v118, v118, v118
	v_fmac_f32_e32 v118, v111, v111
	v_lshlrev_b32_e32 v111, 16, v119
	v_add_f32_e32 v111, v112, v111
	v_and_b32_e32 v112, 0xffff0000, v119
	v_add_f32_e32 v111, v52, v111
	v_add_f32_e32 v112, v113, v112
	v_add_f32_e32 v112, v53, v112
	v_cvt_pk_bf16_f32 v111, v111, v112
	s_nop 0
	v_and_b32_e32 v113, 0xffff0000, v111
	v_lshlrev_b32_e32 v112, 16, v111
	v_mul_f32_e32 v113, v113, v113
	v_fmac_f32_e32 v113, v112, v112
	v_lshlrev_b32_e32 v112, 16, v120
	v_add_f32_e32 v106, v106, v112
	v_and_b32_e32 v112, 0xffff0000, v120
	v_add_f32_e32 v107, v107, v112
	v_add_f32_e32 v107, v43, v107
	v_add_f32_e32 v106, v42, v106
	v_cvt_pk_bf16_f32 v112, v106, v107
	v_add_f32_e32 v113, v118, v113
	v_and_b32_e32 v107, 0xffff0000, v112
	v_lshlrev_b32_e32 v106, 16, v112
	v_mul_f32_e32 v107, v107, v107
	v_fmac_f32_e32 v107, v106, v106
	v_add_f32_e32 v106, v113, v107
	v_lshlrev_b32_e32 v107, 16, v121
	v_add_f32_e32 v107, v108, v107
	v_and_b32_e32 v108, 0xffff0000, v121
	v_add_f32_e32 v108, v109, v108
	v_add_f32_e32 v108, v45, v108
	v_add_f32_e32 v107, v44, v107
	v_cvt_pk_bf16_f32 v113, v107, v108
	global_store_dwordx4 v[116:117], v[110:113], off
	v_and_b32_e32 v108, 0xffff0000, v113
	v_lshlrev_b32_e32 v107, 16, v113
	v_mul_f32_e32 v108, v108, v108
	v_fmac_f32_e32 v108, v107, v107
	v_add_f32_e32 v118, v106, v108
	s_waitcnt vmcnt(12)
	v_mov_b64_e32 v[106:107], v[216:217]
	v_mov_b64_e32 v[108:109], v[218:219]
	global_load_dwordx4 v[216:219], v[198:199], off offset:256
	v_lshlrev_b32_e32 v110, 16, v106
	v_add_f32_e32 v102, v102, v110
	v_and_b32_e32 v106, 0xffff0000, v106
	v_add_f32_e32 v102, v38, v102
	v_add_f32_e32 v103, v103, v106
	v_add_f32_e32 v103, v39, v103
	v_cvt_pk_bf16_f32 v102, v102, v103
	s_nop 0
	v_and_b32_e32 v106, 0xffff0000, v102
	v_lshlrev_b32_e32 v103, 16, v102
	v_mul_f32_e32 v106, v106, v106
	v_fmac_f32_e32 v106, v103, v103
	v_lshlrev_b32_e32 v103, 16, v107
	v_add_f32_e32 v103, v104, v103
	v_and_b32_e32 v104, 0xffff0000, v107
	v_add_f32_e32 v103, v40, v103
	v_add_f32_e32 v104, v105, v104
	v_add_f32_e32 v104, v41, v104
	v_cvt_pk_bf16_f32 v103, v103, v104
	v_add_f32_e32 v106, v118, v106
	v_and_b32_e32 v105, 0xffff0000, v103
	v_lshlrev_b32_e32 v104, 16, v103
	v_mul_f32_e32 v105, v105, v105
	v_fmac_f32_e32 v105, v104, v104
	v_lshlrev_b32_e32 v104, 16, v108
	v_add_f32_e32 v98, v98, v104
	v_and_b32_e32 v104, 0xffff0000, v108
	v_add_f32_e32 v99, v99, v104
	v_add_f32_e32 v99, v27, v99
	v_add_f32_e32 v98, v26, v98
	v_cvt_pk_bf16_f32 v104, v98, v99
	v_add_f32_e32 v105, v106, v105
	v_and_b32_e32 v99, 0xffff0000, v104
	v_lshlrev_b32_e32 v98, 16, v104
	v_mul_f32_e32 v99, v99, v99
	v_fmac_f32_e32 v99, v98, v98
	v_add_f32_e32 v98, v105, v99
	v_lshlrev_b32_e32 v99, 16, v109
	v_add_f32_e32 v99, v100, v99
	v_and_b32_e32 v100, 0xffff0000, v109
	v_add_f32_e32 v100, v101, v100
	v_add_f32_e32 v100, v29, v100
	v_add_f32_e32 v99, v28, v99
	v_cvt_pk_bf16_f32 v105, v99, v100
	global_store_dwordx4 v[116:117], v[102:105], off offset:256
	v_and_b32_e32 v100, 0xffff0000, v105
	v_lshlrev_b32_e32 v99, 16, v105
	v_mul_f32_e32 v100, v100, v100
	v_fmac_f32_e32 v100, v99, v99
	v_add_f32_e32 v98, v98, v100
	ds_bpermute_b32 v99, v134, v98
	s_waitcnt lgkmcnt(0)
	v_add_f32_e32 v98, v98, v99
	ds_bpermute_b32 v99, v135, v98
	s_and_saveexec_b64 s[28:29], s[38:39]
	s_cbranch_execz .LBB0_763
	s_waitcnt lgkmcnt(0)
	v_add_f32_e32 v100, v98, v99
	v_lshlrev_b64 v[98:99], 6, v[114:115]
	v_lshl_add_u64 v[98:99], s[14:15], 0, v[98:99]
	v_lshl_add_u64 v[98:99], s[0:1], 2, v[98:99]
	s_mov_b32 s61, s89
	s_lshl_b32 s60, s46, 2
	v_lshl_add_u64 v[98:99], v[98:99], 0, s[60:61]
	global_store_dword v[98:99], v100, off
; __device__ __forceinline__ unsigned pk2(float lo, float hi) { unsigned r; asm("v_cvt_pk_bf16_f32 %0, %1, %2" : "=v"(r) : "v"(lo), "v"(hi)); return r; }
;     __device__ __forceinline__ void operator()(const pg8::f32x4 (&acc)[2][2][4][2], const pg8::Unit& u, int wr, int wc, int fr, int fq) const {
;     ...
;             for (int m = 0; m < 4; ++m) { const int r = u.pm * 256 + ai * 128 + wr * 64 + m * 16 + fr; bf16* rowp = RB + (size_t)r * ldc + col0;
;                 float ss = 0.f;
; #pragma unroll
;                 for (int bj = 0; bj < 2; ++bj) { const u32x4 old = *(const u32x4*)(rowp + bj * 128); u32x4 w;
; #pragma unroll
;                     for (int x = 0; x < 4; ++x) { const int n = x >> 1, e = (x & 1) * 2;
;                         const float lo = __uint_as_float(old[x] << 16) + acc[ai][bj][m][n][e] + bv[bj][n][e], hi = __uint_as_float(old[x] & 0xffff0000u) + acc[ai][bj][m][n][e + 1] + bv[bj][n][e + 1];
;                         const unsigned pw = pk2(lo, hi); w[x] = pw;
;                         const float rl = __uint_as_float(pw << 16), rh = __uint_as_float(pw & 0xffff0000u); ss += rl * rl + rh * rh; }
;                     *(u32x4*)(rowp + bj * 128) = w; }
;                 ss += __shfl_xor(ss, 16); ss += __shfl_xor(ss, 32);
;                 if (fq == 0) ssq[(size_t)r * 16 + u.pn * 4 + wc] = ss; }
.LBB0_763:
	s_or_b64 exec, exec, s[28:29]
	v_or_b32_e32 v98, 48, v160
	s_waitcnt lgkmcnt(0)
	v_ashrrev_i32_e32 v99, 31, v98
	v_lshlrev_b64 v[100:101], 11, v[98:99]
	v_lshl_add_u64 v[100:101], s[16:17], 0, v[100:101]
	v_lshl_add_u64 v[100:101], v[158:159], 1, v[100:101]
	s_waitcnt vmcnt(13)
	v_mov_b64_e32 v[102:103], v[220:221]
	v_mov_b64_e32 v[104:105], v[222:223]
	global_load_dwordx4 v[220:223], v[200:201], off
	v_lshlrev_b32_e32 v106, 16, v102
	v_add_f32_e32 v94, v94, v106
	v_and_b32_e32 v102, 0xffff0000, v102
	v_add_f32_e32 v94, v50, v94
	v_add_f32_e32 v95, v95, v102
	v_add_f32_e32 v95, v51, v95
	v_cvt_pk_bf16_f32 v94, v94, v95
	s_nop 0
	v_and_b32_e32 v102, 0xffff0000, v94
	v_lshlrev_b32_e32 v95, 16, v94
	v_mul_f32_e32 v102, v102, v102
	v_fmac_f32_e32 v102, v95, v95
	v_lshlrev_b32_e32 v95, 16, v103
	v_add_f32_e32 v95, v96, v95
	v_and_b32_e32 v96, 0xffff0000, v103
	v_add_f32_e32 v95, v52, v95
	v_add_f32_e32 v96, v97, v96
	v_add_f32_e32 v96, v53, v96
	v_cvt_pk_bf16_f32 v95, v95, v96
	s_nop 0
	v_and_b32_e32 v97, 0xffff0000, v95
	v_lshlrev_b32_e32 v96, 16, v95
	v_mul_f32_e32 v97, v97, v97
	v_fmac_f32_e32 v97, v96, v96
	v_lshlrev_b32_e32 v96, 16, v104
	v_add_f32_e32 v90, v90, v96
	v_and_b32_e32 v96, 0xffff0000, v104
	v_add_f32_e32 v91, v91, v96
	v_add_f32_e32 v91, v43, v91
	v_add_f32_e32 v90, v42, v90
	v_cvt_pk_bf16_f32 v96, v90, v91
	v_add_f32_e32 v97, v102, v97
	v_and_b32_e32 v91, 0xffff0000, v96
	v_lshlrev_b32_e32 v90, 16, v96
	v_mul_f32_e32 v91, v91, v91
	v_fmac_f32_e32 v91, v90, v90
	v_add_f32_e32 v90, v97, v91
	v_lshlrev_b32_e32 v91, 16, v105
	v_add_f32_e32 v91, v92, v91
	v_and_b32_e32 v92, 0xffff0000, v105
	v_add_f32_e32 v92, v93, v92
	v_add_f32_e32 v92, v45, v92
	v_add_f32_e32 v91, v44, v91
	v_cvt_pk_bf16_f32 v97, v91, v92
	global_store_dwordx4 v[100:101], v[94:97], off
	v_and_b32_e32 v92, 0xffff0000, v97
	v_lshlrev_b32_e32 v91, 16, v97
	v_mul_f32_e32 v92, v92, v92
	v_fmac_f32_e32 v92, v91, v91
	v_add_f32_e32 v102, v90, v92
	s_waitcnt vmcnt(14)
	v_mov_b64_e32 v[90:91], v[224:225]
	v_mov_b64_e32 v[92:93], v[226:227]
	global_load_dwordx4 v[224:227], v[200:201], off offset:256
	v_lshlrev_b32_e32 v94, 16, v90
	v_add_f32_e32 v86, v86, v94
	v_and_b32_e32 v90, 0xffff0000, v90
	v_add_f32_e32 v86, v38, v86
	v_add_f32_e32 v87, v87, v90
	v_add_f32_e32 v87, v39, v87
	v_cvt_pk_bf16_f32 v86, v86, v87
	s_nop 0
	v_and_b32_e32 v90, 0xffff0000, v86
	v_lshlrev_b32_e32 v87, 16, v86
	v_mul_f32_e32 v90, v90, v90
	v_fmac_f32_e32 v90, v87, v87
	v_lshlrev_b32_e32 v87, 16, v91
	v_add_f32_e32 v87, v88, v87
	v_and_b32_e32 v88, 0xffff0000, v91
	v_add_f32_e32 v87, v40, v87
	v_add_f32_e32 v88, v89, v88
	v_add_f32_e32 v88, v41, v88
	v_cvt_pk_bf16_f32 v87, v87, v88
	v_add_f32_e32 v90, v102, v90
	v_and_b32_e32 v89, 0xffff0000, v87
	v_lshlrev_b32_e32 v88, 16, v87
	v_mul_f32_e32 v89, v89, v89
	v_fmac_f32_e32 v89, v88, v88
	v_lshlrev_b32_e32 v88, 16, v92
	v_add_f32_e32 v82, v82, v88
	v_and_b32_e32 v88, 0xffff0000, v92
	v_add_f32_e32 v83, v83, v88
	v_add_f32_e32 v83, v27, v83
	v_add_f32_e32 v82, v26, v82
	v_cvt_pk_bf16_f32 v88, v82, v83
	v_add_f32_e32 v89, v90, v89
	v_and_b32_e32 v83, 0xffff0000, v88
	v_lshlrev_b32_e32 v82, 16, v88
	v_mul_f32_e32 v83, v83, v83
	v_fmac_f32_e32 v83, v82, v82
	v_add_f32_e32 v82, v89, v83
	v_lshlrev_b32_e32 v83, 16, v93
	v_add_f32_e32 v83, v84, v83
	v_and_b32_e32 v84, 0xffff0000, v93
	v_add_f32_e32 v84, v85, v84
	v_add_f32_e32 v84, v29, v84
	v_add_f32_e32 v83, v28, v83
	v_cvt_pk_bf16_f32 v89, v83, v84
	global_store_dwordx4 v[100:101], v[86:89], off offset:256
	v_and_b32_e32 v84, 0xffff0000, v89
	v_lshlrev_b32_e32 v83, 16, v89
	v_mul_f32_e32 v84, v84, v84
	v_fmac_f32_e32 v84, v83, v83
	v_add_f32_e32 v82, v82, v84
	ds_bpermute_b32 v83, v134, v82
	s_waitcnt lgkmcnt(0)
	v_add_f32_e32 v82, v82, v83
	ds_bpermute_b32 v83, v135, v82
	s_and_saveexec_b64 s[28:29], s[38:39]
	s_cbranch_execz .LBB0_765
	s_waitcnt lgkmcnt(0)
	v_add_f32_e32 v84, v82, v83
	v_lshlrev_b64 v[82:83], 6, v[98:99]
	v_lshl_add_u64 v[82:83], s[14:15], 0, v[82:83]
	v_lshl_add_u64 v[82:83], s[0:1], 2, v[82:83]
	s_mov_b32 s61, s89
	s_lshl_b32 s60, s46, 2
	v_lshl_add_u64 v[82:83], v[82:83], 0, s[60:61]
	global_store_dword v[82:83], v84, off
.LBB0_765:
	s_or_b64 exec, exec, s[28:29]
	v_add_u32_e32 v82, 0x80, v160
	s_waitcnt lgkmcnt(0)
	v_ashrrev_i32_e32 v83, 31, v82
	v_lshlrev_b64 v[84:85], 11, v[82:83]
	v_lshl_add_u64 v[84:85], s[16:17], 0, v[84:85]
	v_lshl_add_u64 v[84:85], v[158:159], 1, v[84:85]
	s_waitcnt vmcnt(15)
	v_mov_b64_e32 v[86:87], v[228:229]
	v_mov_b64_e32 v[88:89], v[230:231]
	v_lshlrev_b32_e32 v90, 16, v86
	v_add_f32_e32 v78, v78, v90
	v_and_b32_e32 v86, 0xffff0000, v86
	v_add_f32_e32 v78, v50, v78
	v_add_f32_e32 v79, v79, v86
	v_add_f32_e32 v79, v51, v79
	v_cvt_pk_bf16_f32 v78, v78, v79
	s_nop 0
	v_and_b32_e32 v86, 0xffff0000, v78
	v_lshlrev_b32_e32 v79, 16, v78
	v_mul_f32_e32 v86, v86, v86
	v_fmac_f32_e32 v86, v79, v79
	v_lshlrev_b32_e32 v79, 16, v87
	v_add_f32_e32 v79, v80, v79
	v_and_b32_e32 v80, 0xffff0000, v87
	v_add_f32_e32 v79, v52, v79
	v_add_f32_e32 v80, v81, v80
	v_add_f32_e32 v80, v53, v80
	v_cvt_pk_bf16_f32 v79, v79, v80
	s_nop 0
	v_and_b32_e32 v81, 0xffff0000, v79
	v_lshlrev_b32_e32 v80, 16, v79
	v_mul_f32_e32 v81, v81, v81
	v_fmac_f32_e32 v81, v80, v80
	v_lshlrev_b32_e32 v80, 16, v88
	v_add_f32_e32 v74, v74, v80
	v_and_b32_e32 v80, 0xffff0000, v88
	v_add_f32_e32 v75, v75, v80
	v_add_f32_e32 v75, v43, v75
	v_add_f32_e32 v74, v42, v74
	v_cvt_pk_bf16_f32 v80, v74, v75
	v_add_f32_e32 v81, v86, v81
	v_and_b32_e32 v75, 0xffff0000, v80
	v_lshlrev_b32_e32 v74, 16, v80
	v_mul_f32_e32 v75, v75, v75
	v_fmac_f32_e32 v75, v74, v74
	v_add_f32_e32 v74, v81, v75
	v_lshlrev_b32_e32 v75, 16, v89
	v_add_f32_e32 v75, v76, v75
	v_and_b32_e32 v76, 0xffff0000, v89
	v_add_f32_e32 v76, v77, v76
	v_add_f32_e32 v76, v45, v76
	v_add_f32_e32 v75, v44, v75
	v_cvt_pk_bf16_f32 v81, v75, v76
	global_store_dwordx4 v[84:85], v[78:81], off
	v_and_b32_e32 v76, 0xffff0000, v81
	v_lshlrev_b32_e32 v75, 16, v81
	v_mul_f32_e32 v76, v76, v76
	v_fmac_f32_e32 v76, v75, v75
	v_add_f32_e32 v86, v74, v76
	s_waitcnt vmcnt(15)
; __device__ __forceinline__ unsigned pk2(float lo, float hi) { unsigned r; asm("v_cvt_pk_bf16_f32 %0, %1, %2" : "=v"(r) : "v"(lo), "v"(hi)); return r; }
;     __device__ __forceinline__ void operator()(const pg8::f32x4 (&acc)[2][2][4][2], const pg8::Unit& u, int wr, int wc, int fr, int fq) const {
;     ...
;             for (int m = 0; m < 4; ++m) { const int r = u.pm * 256 + ai * 128 + wr * 64 + m * 16 + fr; bf16* rowp = RB + (size_t)r * ldc + col0;
;                 float ss = 0.f;
; #pragma unroll
;                 for (int bj = 0; bj < 2; ++bj) { const u32x4 old = *(const u32x4*)(rowp + bj * 128); u32x4 w;
; #pragma unroll
;                     for (int x = 0; x < 4; ++x) { const int n = x >> 1, e = (x & 1) * 2;
;                         const float lo = __uint_as_float(old[x] << 16) + acc[ai][bj][m][n][e] + bv[bj][n][e], hi = __uint_as_float(old[x] & 0xffff0000u) + acc[ai][bj][m][n][e + 1] + bv[bj][n][e + 1];
;                         const unsigned pw = pk2(lo, hi); w[x] = pw;
;                         const float rl = __uint_as_float(pw << 16), rh = __uint_as_float(pw & 0xffff0000u); ss += rl * rl + rh * rh; }
;                     *(u32x4*)(rowp + bj * 128) = w; }
;                 ss += __shfl_xor(ss, 16); ss += __shfl_xor(ss, 32);
;                 if (fq == 0) ssq[(size_t)r * 16 + u.pn * 4 + wc] = ss; }
	v_mov_b64_e32 v[74:75], v[232:233]
	v_mov_b64_e32 v[76:77], v[234:235]
	v_lshlrev_b32_e32 v78, 16, v74
	v_add_f32_e32 v70, v70, v78
	v_and_b32_e32 v74, 0xffff0000, v74
	v_add_f32_e32 v70, v38, v70
	v_add_f32_e32 v71, v71, v74
	v_add_f32_e32 v71, v39, v71
	v_cvt_pk_bf16_f32 v70, v70, v71
	s_nop 0
	v_and_b32_e32 v74, 0xffff0000, v70
	v_lshlrev_b32_e32 v71, 16, v70
	v_mul_f32_e32 v74, v74, v74
	v_fmac_f32_e32 v74, v71, v71
	v_lshlrev_b32_e32 v71, 16, v75
	v_add_f32_e32 v71, v72, v71
	v_and_b32_e32 v72, 0xffff0000, v75
	v_add_f32_e32 v71, v40, v71
	v_add_f32_e32 v72, v73, v72
	v_add_f32_e32 v72, v41, v72
	v_cvt_pk_bf16_f32 v71, v71, v72
	v_add_f32_e32 v74, v86, v74
	v_and_b32_e32 v73, 0xffff0000, v71
	v_lshlrev_b32_e32 v72, 16, v71
	v_mul_f32_e32 v73, v73, v73
	v_fmac_f32_e32 v73, v72, v72
	v_lshlrev_b32_e32 v72, 16, v76
	v_add_f32_e32 v66, v66, v72
	v_and_b32_e32 v72, 0xffff0000, v76
	v_add_f32_e32 v67, v67, v72
	v_add_f32_e32 v67, v27, v67
	v_add_f32_e32 v66, v26, v66
	v_cvt_pk_bf16_f32 v72, v66, v67
	v_add_f32_e32 v73, v74, v73
	v_and_b32_e32 v67, 0xffff0000, v72
	v_lshlrev_b32_e32 v66, 16, v72
	v_mul_f32_e32 v67, v67, v67
	v_fmac_f32_e32 v67, v66, v66
	v_add_f32_e32 v66, v73, v67
	v_lshlrev_b32_e32 v67, 16, v77
	v_add_f32_e32 v67, v68, v67
	v_and_b32_e32 v68, 0xffff0000, v77
	v_add_f32_e32 v68, v69, v68
	v_add_f32_e32 v68, v29, v68
	v_add_f32_e32 v67, v28, v67
	v_cvt_pk_bf16_f32 v73, v67, v68
	global_store_dwordx4 v[84:85], v[70:73], off offset:256
	v_and_b32_e32 v68, 0xffff0000, v73
	v_lshlrev_b32_e32 v67, 16, v73
	v_mul_f32_e32 v68, v68, v68
	v_fmac_f32_e32 v68, v67, v67
	v_add_f32_e32 v66, v66, v68
	ds_bpermute_b32 v67, v134, v66
	s_waitcnt lgkmcnt(0)
	v_add_f32_e32 v66, v66, v67
	ds_bpermute_b32 v67, v135, v66
	s_and_saveexec_b64 s[28:29], s[38:39]
	s_cbranch_execz .LBB0_767
	s_waitcnt lgkmcnt(0)
	v_add_f32_e32 v68, v66, v67
	v_lshlrev_b64 v[66:67], 6, v[82:83]
	v_lshl_add_u64 v[66:67], s[14:15], 0, v[66:67]
	v_lshl_add_u64 v[66:67], s[0:1], 2, v[66:67]
	s_mov_b32 s61, s89
	s_lshl_b32 s60, s46, 2
	v_lshl_add_u64 v[66:67], v[66:67], 0, s[60:61]
	global_store_dword v[66:67], v68, off
.LBB0_767:
	s_or_b64 exec, exec, s[28:29]
	v_add_u32_e32 v66, 0x90, v160
	s_waitcnt lgkmcnt(0)
	v_ashrrev_i32_e32 v67, 31, v66
	v_lshlrev_b64 v[68:69], 11, v[66:67]
	v_lshl_add_u64 v[68:69], s[16:17], 0, v[68:69]
	v_lshl_add_u64 v[68:69], v[158:159], 1, v[68:69]
	s_waitcnt vmcnt(13)
	v_mov_b64_e32 v[70:71], v[204:205]
	v_mov_b64_e32 v[72:73], v[206:207]
	v_lshlrev_b32_e32 v74, 16, v70
	v_add_f32_e32 v62, v62, v74
	v_and_b32_e32 v70, 0xffff0000, v70
	v_add_f32_e32 v62, v50, v62
	v_add_f32_e32 v63, v63, v70
	v_add_f32_e32 v63, v51, v63
	v_cvt_pk_bf16_f32 v62, v62, v63
	s_nop 0
	v_and_b32_e32 v70, 0xffff0000, v62
	v_lshlrev_b32_e32 v63, 16, v62
	v_mul_f32_e32 v70, v70, v70
	v_fmac_f32_e32 v70, v63, v63
	v_lshlrev_b32_e32 v63, 16, v71
	v_add_f32_e32 v63, v64, v63
	v_and_b32_e32 v64, 0xffff0000, v71
	v_add_f32_e32 v63, v52, v63
	v_add_f32_e32 v64, v65, v64
	v_add_f32_e32 v64, v53, v64
	v_cvt_pk_bf16_f32 v63, v63, v64
	s_nop 0
	v_and_b32_e32 v65, 0xffff0000, v63
	v_lshlrev_b32_e32 v64, 16, v63
	v_mul_f32_e32 v65, v65, v65
	v_fmac_f32_e32 v65, v64, v64
	v_lshlrev_b32_e32 v64, 16, v72
	v_add_f32_e32 v58, v58, v64
	v_and_b32_e32 v64, 0xffff0000, v72
	v_add_f32_e32 v59, v59, v64
	v_add_f32_e32 v59, v43, v59
	v_add_f32_e32 v58, v42, v58
	v_cvt_pk_bf16_f32 v64, v58, v59
	v_add_f32_e32 v65, v70, v65
	v_and_b32_e32 v59, 0xffff0000, v64
	v_lshlrev_b32_e32 v58, 16, v64
	v_mul_f32_e32 v59, v59, v59
	v_fmac_f32_e32 v59, v58, v58
	v_add_f32_e32 v58, v65, v59
	v_lshlrev_b32_e32 v59, 16, v73
	v_add_f32_e32 v59, v60, v59
	v_and_b32_e32 v60, 0xffff0000, v73
	v_add_f32_e32 v60, v61, v60
	v_add_f32_e32 v60, v45, v60
	v_add_f32_e32 v59, v44, v59
	v_cvt_pk_bf16_f32 v65, v59, v60
	global_store_dwordx4 v[68:69], v[62:65], off
	v_and_b32_e32 v60, 0xffff0000, v65
	v_lshlrev_b32_e32 v59, 16, v65
	v_mul_f32_e32 v60, v60, v60
	v_fmac_f32_e32 v60, v59, v59
	v_add_f32_e32 v70, v58, v60
	s_waitcnt vmcnt(12)
	v_mov_b64_e32 v[58:59], v[208:209]
	v_mov_b64_e32 v[60:61], v[210:211]
	v_lshlrev_b32_e32 v62, 16, v58
	v_add_f32_e32 v54, v54, v62
	v_and_b32_e32 v58, 0xffff0000, v58
	v_add_f32_e32 v54, v38, v54
	v_add_f32_e32 v55, v55, v58
	v_add_f32_e32 v55, v39, v55
	v_cvt_pk_bf16_f32 v54, v54, v55
	s_nop 0
	v_and_b32_e32 v58, 0xffff0000, v54
	v_lshlrev_b32_e32 v55, 16, v54
	v_mul_f32_e32 v58, v58, v58
	v_fmac_f32_e32 v58, v55, v55
	v_lshlrev_b32_e32 v55, 16, v59
	v_add_f32_e32 v55, v56, v55
	v_and_b32_e32 v56, 0xffff0000, v59
	v_add_f32_e32 v55, v40, v55
	v_add_f32_e32 v56, v57, v56
	v_add_f32_e32 v56, v41, v56
	v_cvt_pk_bf16_f32 v55, v55, v56
	v_add_f32_e32 v58, v70, v58
	v_and_b32_e32 v57, 0xffff0000, v55
	v_lshlrev_b32_e32 v56, 16, v55
	v_mul_f32_e32 v57, v57, v57
	v_fmac_f32_e32 v57, v56, v56
	v_lshlrev_b32_e32 v56, 16, v60
	v_add_f32_e32 v46, v46, v56
	v_and_b32_e32 v56, 0xffff0000, v60
	v_add_f32_e32 v47, v47, v56
	v_add_f32_e32 v47, v27, v47
	v_add_f32_e32 v46, v26, v46
	v_cvt_pk_bf16_f32 v56, v46, v47
	v_add_f32_e32 v57, v58, v57
	v_and_b32_e32 v47, 0xffff0000, v56
	v_lshlrev_b32_e32 v46, 16, v56
	v_mul_f32_e32 v47, v47, v47
	v_fmac_f32_e32 v47, v46, v46
	v_add_f32_e32 v46, v57, v47
	v_lshlrev_b32_e32 v47, 16, v61
	v_add_f32_e32 v47, v48, v47
	v_and_b32_e32 v48, 0xffff0000, v61
	v_add_f32_e32 v48, v49, v48
	v_add_f32_e32 v48, v29, v48
	v_add_f32_e32 v47, v28, v47
	v_cvt_pk_bf16_f32 v57, v47, v48
	global_store_dwordx4 v[68:69], v[54:57], off offset:256
	v_and_b32_e32 v48, 0xffff0000, v57
	v_lshlrev_b32_e32 v47, 16, v57
	v_mul_f32_e32 v48, v48, v48
	v_fmac_f32_e32 v48, v47, v47
	v_add_f32_e32 v46, v46, v48
	ds_bpermute_b32 v47, v134, v46
	s_waitcnt lgkmcnt(0)
	v_add_f32_e32 v46, v46, v47
	ds_bpermute_b32 v47, v135, v46
	s_and_saveexec_b64 s[28:29], s[38:39]
	s_cbranch_execz .LBB0_769
	s_waitcnt lgkmcnt(0)
	v_add_f32_e32 v48, v46, v47
	v_lshlrev_b64 v[46:47], 6, v[66:67]
	v_lshl_add_u64 v[46:47], s[14:15], 0, v[46:47]
	v_lshl_add_u64 v[46:47], s[0:1], 2, v[46:47]
	s_mov_b32 s61, s89
	s_lshl_b32 s60, s46, 2
	v_lshl_add_u64 v[46:47], v[46:47], 0, s[60:61]
	global_store_dword v[46:47], v48, off
; __device__ __forceinline__ unsigned pk2(float lo, float hi) { unsigned r; asm("v_cvt_pk_bf16_f32 %0, %1, %2" : "=v"(r) : "v"(lo), "v"(hi)); return r; }
;     __device__ __forceinline__ void operator()(const pg8::f32x4 (&acc)[2][2][4][2], const pg8::Unit& u, int wr, int wc, int fr, int fq) const {
;     ...
;             for (int m = 0; m < 4; ++m) { const int r = u.pm * 256 + ai * 128 + wr * 64 + m * 16 + fr; bf16* rowp = RB + (size_t)r * ldc + col0;
;                 float ss = 0.f;
; #pragma unroll
;                 for (int bj = 0; bj < 2; ++bj) { const u32x4 old = *(const u32x4*)(rowp + bj * 128); u32x4 w;
; #pragma unroll
;                     for (int x = 0; x < 4; ++x) { const int n = x >> 1, e = (x & 1) * 2;
;                         const float lo = __uint_as_float(old[x] << 16) + acc[ai][bj][m][n][e] + bv[bj][n][e], hi = __uint_as_float(old[x] & 0xffff0000u) + acc[ai][bj][m][n][e + 1] + bv[bj][n][e + 1];
;                         const unsigned pw = pk2(lo, hi); w[x] = pw;
;                         const float rl = __uint_as_float(pw << 16), rh = __uint_as_float(pw & 0xffff0000u); ss += rl * rl + rh * rh; }
;                     *(u32x4*)(rowp + bj * 128) = w; }
;                 ss += __shfl_xor(ss, 16); ss += __shfl_xor(ss, 32);
;                 if (fq == 0) ssq[(size_t)r * 16 + u.pn * 4 + wc] = ss; }
.LBB0_769:
	s_or_b64 exec, exec, s[28:29]
	v_add_u32_e32 v46, 0xa0, v160
	s_waitcnt lgkmcnt(0)
	v_ashrrev_i32_e32 v47, 31, v46
	v_lshlrev_b64 v[48:49], 11, v[46:47]
	v_lshl_add_u64 v[48:49], s[16:17], 0, v[48:49]
	v_lshl_add_u64 v[48:49], v[158:159], 1, v[48:49]
	s_waitcnt vmcnt(11)
	v_mov_b64_e32 v[54:55], v[212:213]
	v_mov_b64_e32 v[56:57], v[214:215]
	v_lshlrev_b32_e32 v58, 16, v54
	v_add_f32_e32 v34, v34, v58
	v_and_b32_e32 v54, 0xffff0000, v54
	v_add_f32_e32 v34, v50, v34
	v_add_f32_e32 v35, v35, v54
	v_add_f32_e32 v35, v51, v35
	v_cvt_pk_bf16_f32 v34, v34, v35
	s_nop 0
	v_and_b32_e32 v54, 0xffff0000, v34
	v_lshlrev_b32_e32 v35, 16, v34
	v_mul_f32_e32 v54, v54, v54
	v_fmac_f32_e32 v54, v35, v35
	v_lshlrev_b32_e32 v35, 16, v55
	v_add_f32_e32 v35, v36, v35
	v_and_b32_e32 v36, 0xffff0000, v55
	v_add_f32_e32 v35, v52, v35
	v_add_f32_e32 v36, v37, v36
	v_add_f32_e32 v36, v53, v36
	v_cvt_pk_bf16_f32 v35, v35, v36
	s_nop 0
	v_and_b32_e32 v37, 0xffff0000, v35
	v_lshlrev_b32_e32 v36, 16, v35
	v_mul_f32_e32 v37, v37, v37
	v_fmac_f32_e32 v37, v36, v36
	v_lshlrev_b32_e32 v36, 16, v56
	v_add_f32_e32 v30, v30, v36
	v_and_b32_e32 v36, 0xffff0000, v56
	v_add_f32_e32 v31, v31, v36
	v_add_f32_e32 v31, v43, v31
	v_add_f32_e32 v30, v42, v30
	v_cvt_pk_bf16_f32 v36, v30, v31
	v_add_f32_e32 v37, v54, v37
	v_and_b32_e32 v31, 0xffff0000, v36
	v_lshlrev_b32_e32 v30, 16, v36
	v_mul_f32_e32 v31, v31, v31
	v_fmac_f32_e32 v31, v30, v30
	v_add_f32_e32 v30, v37, v31
	v_lshlrev_b32_e32 v31, 16, v57
	v_add_f32_e32 v31, v32, v31
	v_and_b32_e32 v32, 0xffff0000, v57
	v_add_f32_e32 v32, v33, v32
	v_add_f32_e32 v32, v45, v32
	v_add_f32_e32 v31, v44, v31
	v_cvt_pk_bf16_f32 v37, v31, v32
	global_store_dwordx4 v[48:49], v[34:37], off
	v_and_b32_e32 v32, 0xffff0000, v37
	v_lshlrev_b32_e32 v31, 16, v37
	v_mul_f32_e32 v32, v32, v32
	v_fmac_f32_e32 v32, v31, v31
	v_add_f32_e32 v54, v30, v32
	s_waitcnt vmcnt(10)
	v_mov_b64_e32 v[30:31], v[216:217]
	v_mov_b64_e32 v[32:33], v[218:219]
	v_lshlrev_b32_e32 v34, 16, v30
	v_add_f32_e32 v22, v22, v34
	v_and_b32_e32 v30, 0xffff0000, v30
	v_add_f32_e32 v22, v38, v22
	v_add_f32_e32 v23, v23, v30
	v_add_f32_e32 v23, v39, v23
	v_cvt_pk_bf16_f32 v22, v22, v23
	s_nop 0
	v_and_b32_e32 v30, 0xffff0000, v22
	v_lshlrev_b32_e32 v23, 16, v22
	v_mul_f32_e32 v30, v30, v30
	v_fmac_f32_e32 v30, v23, v23
	v_lshlrev_b32_e32 v23, 16, v31
	v_add_f32_e32 v23, v24, v23
	v_and_b32_e32 v24, 0xffff0000, v31
	v_add_f32_e32 v23, v40, v23
	v_add_f32_e32 v24, v25, v24
	v_add_f32_e32 v24, v41, v24
	v_cvt_pk_bf16_f32 v23, v23, v24
	v_add_f32_e32 v30, v54, v30
	v_and_b32_e32 v25, 0xffff0000, v23
	v_lshlrev_b32_e32 v24, 16, v23
	v_mul_f32_e32 v25, v25, v25
	v_fmac_f32_e32 v25, v24, v24
	v_lshlrev_b32_e32 v24, 16, v32
	v_add_f32_e32 v18, v18, v24
	v_and_b32_e32 v24, 0xffff0000, v32
	v_add_f32_e32 v19, v19, v24
	v_add_f32_e32 v19, v27, v19
	v_add_f32_e32 v18, v26, v18
	v_cvt_pk_bf16_f32 v24, v18, v19
	v_add_f32_e32 v25, v30, v25
	v_and_b32_e32 v19, 0xffff0000, v24
	v_lshlrev_b32_e32 v18, 16, v24
	v_mul_f32_e32 v19, v19, v19
	v_fmac_f32_e32 v19, v18, v18
	v_add_f32_e32 v18, v25, v19
	v_lshlrev_b32_e32 v19, 16, v33
	v_add_f32_e32 v19, v20, v19
	v_and_b32_e32 v20, 0xffff0000, v33
	v_add_f32_e32 v20, v21, v20
	v_add_f32_e32 v20, v29, v20
	v_add_f32_e32 v19, v28, v19
	v_cvt_pk_bf16_f32 v25, v19, v20
	global_store_dwordx4 v[48:49], v[22:25], off offset:256
	v_and_b32_e32 v20, 0xffff0000, v25
	v_lshlrev_b32_e32 v19, 16, v25
	v_mul_f32_e32 v20, v20, v20
	v_fmac_f32_e32 v20, v19, v19
	v_add_f32_e32 v18, v18, v20
	ds_bpermute_b32 v19, v134, v18
	s_waitcnt lgkmcnt(0)
	v_add_f32_e32 v18, v18, v19
	ds_bpermute_b32 v19, v135, v18
	s_and_saveexec_b64 s[28:29], s[38:39]
	s_cbranch_execz .LBB0_771
	s_waitcnt lgkmcnt(0)
	v_add_f32_e32 v20, v18, v19
	v_lshlrev_b64 v[18:19], 6, v[46:47]
	v_lshl_add_u64 v[18:19], s[14:15], 0, v[18:19]
	v_lshl_add_u64 v[18:19], s[0:1], 2, v[18:19]
	s_mov_b32 s61, s89
	s_lshl_b32 s60, s46, 2
	v_lshl_add_u64 v[18:19], v[18:19], 0, s[60:61]
	global_store_dword v[18:19], v20, off
; __device__ __forceinline__ unsigned pk2(float lo, float hi) { unsigned r; asm("v_cvt_pk_bf16_f32 %0, %1, %2" : "=v"(r) : "v"(lo), "v"(hi)); return r; }
;     __device__ __forceinline__ void operator()(const pg8::f32x4 (&acc)[2][2][4][2], const pg8::Unit& u, int wr, int wc, int fr, int fq) const {
;     ...
;             for (int m = 0; m < 4; ++m) { const int r = u.pm * 256 + ai * 128 + wr * 64 + m * 16 + fr; bf16* rowp = RB + (size_t)r * ldc + col0;
;                 float ss = 0.f;
; #pragma unroll
;                 for (int bj = 0; bj < 2; ++bj) { const u32x4 old = *(const u32x4*)(rowp + bj * 128); u32x4 w;
; #pragma unroll
;                     for (int x = 0; x < 4; ++x) { const int n = x >> 1, e = (x & 1) * 2;
;                         const float lo = __uint_as_float(old[x] << 16) + acc[ai][bj][m][n][e] + bv[bj][n][e], hi = __uint_as_float(old[x] & 0xffff0000u) + acc[ai][bj][m][n][e + 1] + bv[bj][n][e + 1];
;                         const unsigned pw = pk2(lo, hi); w[x] = pw;
;                         const float rl = __uint_as_float(pw << 16), rh = __uint_as_float(pw & 0xffff0000u); ss += rl * rl + rh * rh; }
;                     *(u32x4*)(rowp + bj * 128) = w; }
;                 ss += __shfl_xor(ss, 16); ss += __shfl_xor(ss, 32);
;                 if (fq == 0) ssq[(size_t)r * 16 + u.pn * 4 + wc] = ss; }
.LBB0_771:
	s_or_b64 exec, exec, s[28:29]
	v_add_u32_e32 v18, 0xb0, v160
	s_waitcnt lgkmcnt(0)
	v_ashrrev_i32_e32 v19, 31, v18
	v_lshlrev_b64 v[20:21], 11, v[18:19]
	v_lshl_add_u64 v[20:21], s[16:17], 0, v[20:21]
	v_lshl_add_u64 v[20:21], v[158:159], 1, v[20:21]
	s_waitcnt vmcnt(9)
	v_mov_b64_e32 v[22:23], v[220:221]
	v_mov_b64_e32 v[24:25], v[222:223]
	v_lshlrev_b32_e32 v30, 16, v22
	v_add_f32_e32 v14, v14, v30
	v_and_b32_e32 v22, 0xffff0000, v22
	v_add_f32_e32 v14, v50, v14
	v_add_f32_e32 v15, v15, v22
	v_add_f32_e32 v15, v51, v15
	v_cvt_pk_bf16_f32 v14, v14, v15
	s_nop 0
	v_and_b32_e32 v22, 0xffff0000, v14
	v_lshlrev_b32_e32 v15, 16, v14
	v_mul_f32_e32 v22, v22, v22
	v_fmac_f32_e32 v22, v15, v15
	v_lshlrev_b32_e32 v15, 16, v23
	v_add_f32_e32 v15, v16, v15
	v_and_b32_e32 v16, 0xffff0000, v23
	v_add_f32_e32 v15, v52, v15
	v_add_f32_e32 v16, v17, v16
	v_add_f32_e32 v16, v53, v16
	v_cvt_pk_bf16_f32 v15, v15, v16
	s_nop 0
	v_and_b32_e32 v17, 0xffff0000, v15
	v_lshlrev_b32_e32 v16, 16, v15
	v_mul_f32_e32 v17, v17, v17
	v_fmac_f32_e32 v17, v16, v16
	v_lshlrev_b32_e32 v16, 16, v24
	v_add_f32_e32 v10, v10, v16
	v_and_b32_e32 v16, 0xffff0000, v24
	v_add_f32_e32 v11, v11, v16
	v_add_f32_e32 v11, v43, v11
	v_add_f32_e32 v10, v42, v10
	v_cvt_pk_bf16_f32 v16, v10, v11
	v_add_f32_e32 v17, v22, v17
	v_and_b32_e32 v11, 0xffff0000, v16
	v_lshlrev_b32_e32 v10, 16, v16
	v_mul_f32_e32 v11, v11, v11
	v_fmac_f32_e32 v11, v10, v10
	v_add_f32_e32 v10, v17, v11
	v_lshlrev_b32_e32 v11, 16, v25
	v_add_f32_e32 v11, v12, v11
	v_and_b32_e32 v12, 0xffff0000, v25
	v_add_f32_e32 v12, v13, v12
	v_add_f32_e32 v12, v45, v12
	v_add_f32_e32 v11, v44, v11
	v_cvt_pk_bf16_f32 v17, v11, v12
	global_store_dwordx4 v[20:21], v[14:17], off
	v_and_b32_e32 v12, 0xffff0000, v17
	v_lshlrev_b32_e32 v11, 16, v17
	v_mul_f32_e32 v12, v12, v12
	v_fmac_f32_e32 v12, v11, v11
	v_add_f32_e32 v22, v10, v12
	s_waitcnt vmcnt(8)
	v_mov_b64_e32 v[10:11], v[224:225]
	v_mov_b64_e32 v[12:13], v[226:227]
	v_lshlrev_b32_e32 v14, 16, v10
	v_add_f32_e32 v6, v6, v14
	v_and_b32_e32 v10, 0xffff0000, v10
	v_add_f32_e32 v6, v38, v6
	v_add_f32_e32 v7, v7, v10
	v_add_f32_e32 v7, v39, v7
	v_cvt_pk_bf16_f32 v6, v6, v7
	s_nop 0
	v_and_b32_e32 v10, 0xffff0000, v6
	v_lshlrev_b32_e32 v7, 16, v6
	v_mul_f32_e32 v10, v10, v10
	v_fmac_f32_e32 v10, v7, v7
	v_lshlrev_b32_e32 v7, 16, v11
	v_add_f32_e32 v7, v8, v7
	v_and_b32_e32 v8, 0xffff0000, v11
	v_add_f32_e32 v7, v40, v7
	v_add_f32_e32 v8, v9, v8
	v_add_f32_e32 v8, v41, v8
	v_cvt_pk_bf16_f32 v7, v7, v8
	v_add_f32_e32 v10, v22, v10
	v_and_b32_e32 v9, 0xffff0000, v7
	v_lshlrev_b32_e32 v8, 16, v7
	v_mul_f32_e32 v9, v9, v9
	v_fmac_f32_e32 v9, v8, v8
	v_lshlrev_b32_e32 v8, 16, v12
	v_add_f32_e32 v2, v2, v8
	v_and_b32_e32 v8, 0xffff0000, v12
	v_add_f32_e32 v3, v3, v8
	v_add_f32_e32 v3, v27, v3
	v_add_f32_e32 v2, v26, v2
	v_cvt_pk_bf16_f32 v8, v2, v3
	v_add_f32_e32 v9, v10, v9
	v_and_b32_e32 v3, 0xffff0000, v8
	v_lshlrev_b32_e32 v2, 16, v8
	v_mul_f32_e32 v3, v3, v3
	v_fmac_f32_e32 v3, v2, v2
	v_add_f32_e32 v2, v9, v3
	v_lshlrev_b32_e32 v3, 16, v13
	v_add_f32_e32 v3, v4, v3
	v_and_b32_e32 v4, 0xffff0000, v13
	v_add_f32_e32 v4, v5, v4
	v_add_f32_e32 v4, v29, v4
	v_add_f32_e32 v3, v28, v3
	v_cvt_pk_bf16_f32 v9, v3, v4
	global_store_dwordx4 v[20:21], v[6:9], off offset:256
	v_and_b32_e32 v4, 0xffff0000, v9
	v_lshlrev_b32_e32 v3, 16, v9
	v_mul_f32_e32 v4, v4, v4
	v_fmac_f32_e32 v4, v3, v3
	v_add_f32_e32 v2, v2, v4
	ds_bpermute_b32 v3, v134, v2
	s_waitcnt lgkmcnt(0)
	v_add_f32_e32 v2, v2, v3
	ds_bpermute_b32 v3, v135, v2
	s_and_saveexec_b64 s[28:29], s[38:39]
	s_cbranch_execz .LBB0_773
	s_waitcnt lgkmcnt(0)
	v_add_f32_e32 v4, v2, v3
	v_lshlrev_b64 v[2:3], 6, v[18:19]
	v_lshl_add_u64 v[2:3], s[14:15], 0, v[2:3]
	v_lshl_add_u64 v[2:3], s[0:1], 2, v[2:3]
	s_mov_b32 s1, s89
	s_lshl_b32 s0, s46, 2
	v_lshl_add_u64 v[2:3], v[2:3], 0, s[0:1]
	global_store_dword v[2:3], v4, off
